# ret_out item tail: SG/HF/HB/GG loads batched (8 serialized round trips -> 2)
# speedup vs baseline: 1.0452x; 1.0104x over previous
; #define LAS __attribute__((address_space(3)))
; __device__ __forceinline__ void ret_prefetch(const Frame& F, int it, int nchu, RetPre& P) {
;     const int bh = it / nchu, mc = it - bh * nchu + (NCH - nchu), h = bh & 7, b = bh >> 3;
;     const int tid = F.tid;
;     const size_t rowbase = (size_t)b * TB + 128 * mc;
; #pragma unroll
;     for (int i = 0; i < 2; ++i) {
;         const int u = tid + i * NTHREADS, r = u >> 3, c8 = (u & 7) * 8;
;         P.k[i] = *(const u32x4*)(WSB(WS_KN) + (rowbase + r) * 512 + h * 64 + c8);
;         P.sf[i] = *(const u32x4*)(WSB(WS_ST) + ((((size_t)(b * NH + h) * 2 + 0) * NCH + mc) * DV + r) * DK + c8);
;         P.sb[i] = *(const u32x4*)(WSB(WS_ST) + ((((size_t)(b * NH + h) * 2 + 1) * NCH + mc) * DV + r) * DK + c8);
;     }
; #pragma unroll
;     for (int i = 0; i < 4; ++i) {
;         const int u = tid + i * NTHREADS, r = u >> 4, c8 = (u & 15) * 8;
;         P.vt[i] = *(const u32x4*)(WSB(WS_VT) + ((size_t)(b * NH + h) * DV + r) * TB + 128 * mc + c8);
;     }
; __device__ __forceinline__ void ret_out_phase(const Args& A, Frame& F, int l, bool lastl, bf16_t* ARET, bf16_t* ALRU) {
;     ...
;     for (int jx = 0; jx < nmy; ++jx) {
;         const int it = F.bid + jx * F.G, itn = (jx + 1 < nmy) ? it + F.G : it;
;         const int bh = it / NCHU, mc = it - bh * NCHU + (NCH - NCHU), h = bh & 7, b = bh >> 3;
;         const size_t rowbase = (size_t)b * TB + 128 * mc;
;         __syncthreads();
; #pragma unroll
;         for (int i = 0; i < 2; ++i) {
;             const int u = tid + i * NTHREADS, r = u >> 3, c8 = (u & 7) * 8;
;             *(LAS u32x4*)(ks_ + r * 72 + c8) = P.k[i]; *(LAS u32x4*)(sfs + r * 72 + c8) = P.sf[i]; *(LAS u32x4*)(sbs + r * 72 + c8) = P.sb[i];
;         }
; #pragma unroll
;         for (int i = 0; i < 4; ++i) { const int u = tid + i * NTHREADS, r = u >> 4, c8 = (u & 15) * 8; *(LAS u32x4*)(vts + r * 136 + c8) = P.vt[i]; }
;         bf16x8 qf[2];
; #pragma unroll
;         for (int ks = 0; ks < 2; ++ks) qf[ks] = *(const bf16x8*)(WSB(WS_Q) + (rowbase + 16 * w + fr) * 512 + h * 64 + 32 * ks + 8 * fq);
;         __syncthreads();
;         ret_prefetch(F, itn, NCHU, P);
;         const float l2f = log2_gamma(A, F, l, 0, h), l2b = log2_gamma(A, F, l, 1, h);
.LBB0_30:
	s_add_i32 s39, s39, 1
	s_cmp_lt_i32 s39, s37
	s_cselect_b32 s2, s34, 0
	s_abs_i32 s5, vcc_hi
	s_mul_hi_u32 s8, s5, s45
	s_mul_i32 s9, s8, s20
	s_sub_i32 s5, s5, s9
	s_ashr_i32 s4, vcc_hi, 31
	s_add_i32 s9, s8, 1
	s_sub_i32 s25, s5, s20
	s_cmp_ge_u32 s5, s20
	s_cselect_b32 s8, s9, s8
	s_cselect_b32 s5, s25, s5
	s_add_i32 s9, s8, 1
	s_cmp_ge_u32 s5, s20
	s_cselect_b32 s5, s9, s8
	s_xor_b32 s5, s5, s4
	s_sub_i32 s4, s5, s4
	s_not_b32 s5, s4
	s_mul_i32 s5, vcc_lo, s5
	s_ashr_i32 s8, s4, 3
	s_add_i32 s5, s61, s5
	s_ashr_i32 s9, s5, 31
	s_add_i32 s25, s2, vcc_hi
	s_mul_hi_i32 s52, s8, 0x900
	s_mulk_i32 s8, 0x900
	s_and_b32 s2, s4, 7
	s_add_u32 s8, s8, s5
	s_addc_u32 s9, s52, s9
	s_abs_i32 s5, s25
	s_mul_hi_u32 s52, s5, s45
	s_mul_i32 s53, s52, s20
	s_sub_i32 s5, s5, s53
	s_lshl_b32 s82, s2, 7
	s_ashr_i32 s4, s25, 31
	s_add_i32 s53, s52, 1
	s_sub_i32 s58, s5, s20
	s_cmp_ge_u32 s5, s20
	s_cselect_b32 s52, s53, s52
	s_cselect_b32 s5, s58, s5
	s_add_i32 s53, s52, 1
	s_cmp_ge_u32 s5, s20
	s_cselect_b32 s5, s53, s52
	s_xor_b32 s5, s5, s4
	s_sub_i32 s4, s5, s4
	s_not_b32 s5, s4
	s_mul_i32 s5, s20, s5
	s_add_i32 s5, s25, s5
	s_barrier
	s_waitcnt vmcnt(0)
	ds_write_b128 v134, v[6:9]
	ds_write_b128 v134, v[10:13] offset:53248
	ds_write_b128 v135, v[2:5]
	ds_write_b128 v136, v[22:25]
	ds_write_b128 v136, v[26:29] offset:53248
	ds_write_b128 v137, v[34:37]
	v_lshl_add_u64 v[2:3], v[122:123], 0, s[8:9]
	s_add_i32 s25, s5, 18
	v_lshlrev_b64 v[2:3], 10, v[2:3]
	s_ashr_i32 s5, s4, 3
	s_lshl_b32 s72, s25, 7
	v_lshl_add_u64 v[2:3], s[48:49], 0, v[2:3]
	s_mul_hi_i32 s52, s5, 0x900
	s_mulk_i32 s5, 0x900
	s_ashr_i32 s73, s72, 31
	v_lshl_add_u64 v[2:3], v[2:3], 0, s[82:83]
	s_add_u32 s92, s5, s72
	ds_write_b128 v245, v[14:17] offset:18432
	ds_write_b128 v246, v[18:21] offset:18432
	ds_write_b128 v247, v[30:33] offset:18432
	ds_write_b128 v248, v[38:41] offset:18432
	v_lshl_add_u64 v[2:3], v[2:3], 0, v[0:1]
	s_addc_u32 s93, s52, s73
	s_ashr_i32 s5, s4, 31
	s_mul_i32 s52, s4, 36
	s_ashr_i32 s58, s25, 31
	global_load_dwordx4 v[46:49], v[2:3], off
	global_load_dwordx4 v[42:45], v[2:3], off offset:64
	s_mul_hi_i32 s53, s4, 36
	s_add_u32 s52, s52, s25
	v_lshl_add_u64 v[2:3], s[92:93], 0, v[116:117]
	v_lshl_add_u64 v[14:15], s[92:93], 0, v[114:115]
	s_addc_u32 s53, s53, s58
	v_lshlrev_b64 v[2:3], 10, v[2:3]
	s_lshl_b32 s25, s4, 7
	v_lshlrev_b64 v[14:15], 10, v[14:15]
	s_lshl_b64 s[52:53], s[52:53], 14
	v_lshl_add_u64 v[2:3], s[6:7], 0, v[2:3]
	s_and_b32 s78, s25, 0x380
	s_mov_b32 s79, s83
	v_lshl_add_u64 v[14:15], s[6:7], 0, v[14:15]
	v_lshl_add_u64 v[2:3], v[2:3], 0, s[78:79]
	v_mov_b32_e32 v129, v1
	s_add_u32 s76, s62, s52
	v_lshl_add_u64 v[14:15], v[14:15], 0, s[78:79]
	v_lshl_add_u64 v[2:3], v[2:3], 0, v[128:129]
	s_addc_u32 s77, s63, s53
	v_lshl_add_u64 v[14:15], v[14:15], 0, v[128:129]
	s_waitcnt lgkmcnt(0)
	s_barrier
	global_load_dwordx4 v[6:9], v[2:3], off
	global_load_dwordx4 v[22:25], v[14:15], off
	v_lshl_add_u64 v[2:3], s[76:77], 0, v[120:121]
	s_add_u32 s74, s65, s52
	v_lshl_add_u64 v[14:15], s[76:77], 0, v[118:119]
	v_lshl_add_u64 v[2:3], v[2:3], 0, v[128:129]
	s_addc_u32 s75, s19, s53
	v_lshl_add_u64 v[14:15], v[14:15], 0, v[128:129]
	global_load_dwordx4 v[10:13], v[2:3], off
	global_load_dwordx4 v[26:29], v[14:15], off
	v_lshl_add_u64 v[2:3], s[74:75], 0, v[120:121]
	v_lshl_add_u64 v[14:15], s[74:75], 0, v[118:119]
	v_lshl_add_u64 v[2:3], v[2:3], 0, v[128:129]
	v_lshl_add_u64 v[14:15], v[14:15], 0, v[128:129]
	s_lshl_b64 s[74:75], s[4:5], 7
	global_load_dwordx4 v[2:5], v[2:3], off
	v_mov_b64_e32 v[38:39], s[54:55]
	global_load_dwordx4 v[34:37], v[14:15], off
	v_lshl_add_u64 v[14:15], s[74:75], 0, v[106:107]
	v_lshl_add_u64 v[18:19], s[74:75], 0, v[108:109]
	v_lshl_add_u64 v[30:31], s[74:75], 0, v[110:111]
	v_lshl_add_u64 v[50:51], s[74:75], 0, v[112:113]
	v_mad_u64_u32 v[16:17], s[4:5], v14, s96, v[38:39]
	v_mad_u64_u32 v[20:21], s[52:53], v18, s96, v[38:39]
	v_mad_u64_u32 v[32:33], s[52:53], v30, s96, v[38:39]
	v_mad_u64_u32 v[38:39], s[52:53], v50, s96, v[38:39]
	s_load_dwordx2 s[74:75], s[46:47], 0x60
	v_mad_i32_i24 v17, v15, s96, v17
	s_lshl_b64 s[4:5], s[72:73], 1
	v_mad_i32_i24 v21, v19, s96, v21
	v_mad_i32_i24 v33, v31, s96, v33
	v_mad_i32_i24 v39, v51, s96, v39
	v_lshl_add_u64 v[14:15], v[16:17], 0, s[4:5]
	v_lshl_add_u64 v[18:19], v[20:21], 0, s[4:5]
	v_lshl_add_u64 v[30:31], v[32:33], 0, s[4:5]
	v_lshl_add_u64 v[38:39], v[38:39], 0, s[4:5]
	s_or_b32 s4, s2, s64
	s_ashr_i32 s5, s4, 31
	s_lshl_b64 s[4:5], s[4:5], 2
	s_waitcnt lgkmcnt(0)
	s_add_u32 s78, s74, s4
	s_addc_u32 s79, s75, s5
	global_load_dword v50, v1, s[78:79]
	s_mov_b32 s76, 0xb2a5705f
	s_mov_b32 s77, 0x42ce8ed0
	s_mov_b32 s58, 0xc2b17218
	s_mov_b32 s25, 0x3f2aaaab
	s_mov_b32 s72, 0x7f800000
	s_mov_b32 s73, 0x33800000
	v_lshlrev_b32_e32 v40, 1, v104
	v_mov_b32_e32 v41, v1
	v_lshl_add_u64 v[14:15], v[14:15], 0, v[40:41]
	v_lshl_add_u64 v[18:19], v[18:19], 0, v[40:41]
	v_lshl_add_u64 v[30:31], v[30:31], 0, v[40:41]
	v_lshl_add_u64 v[38:39], v[38:39], 0, v[40:41]
	global_load_dwordx4 v[14:17], v[14:15], off
	v_readlane_b32 s4, v254, 38
	global_load_dwordx4 v[18:21], v[18:19], off
	v_readlane_b32 s5, v254, 39
	global_load_dwordx4 v[30:33], v[30:31], off
	v_add_u32_e32 v82, 0x4800, v230
	global_load_dwordx4 v[38:41], v[38:39], off
	s_mov_b32 s53, s64
	s_waitcnt vmcnt(4)
; __device__ __forceinline__ float softplusf_(float x) { return fmaxf(x, 0.f) + log1pf(expf(-fabsf(x))); }
; __device__ __forceinline__ float log2_gamma(const Args& A, const Frame& F, int l, int dir, int h) {
;     const float x = GIN(12)[(l * 2 + dir) * NH + h];
;     return -softplusf_(-x) * 1.4426950408889634f;
; }
	v_max_f32_e64 v51, -v50, -v50
	v_max_f32_e32 v66, 0, v51
	v_mul_f32_e64 v51, |v50|, s59
	v_fma_f32 v52, |v50|, s59, -v51
	v_rndne_f32_e32 v53, v51
	v_fma_f32 v52, |v50|, s76, v52
	v_sub_f32_e32 v51, v51, v53
	v_add_f32_e32 v51, v51, v52
	v_exp_f32_e32 v51, v51
	v_cvt_i32_f32_e32 v52, v53
	v_cmp_ngt_f32_e64 s[74:75], |v50|, s77
	v_ldexp_f32 v51, v51, v52
	s_nop 0
	v_cndmask_b32_e64 v51, 0, v51, s[74:75]
	v_cmp_nlt_f32_e64 s[74:75], |v50|, s58
	s_nop 1
	v_cndmask_b32_e64 v67, v182, v51, s[74:75]
	v_add_f32_e32 v52, 1.0, v67
	v_add_f32_e32 v50, -1.0, v52
	v_sub_f32_e32 v51, v50, v52
	v_add_f32_e32 v51, 1.0, v51
	v_sub_f32_e32 v50, v67, v50
	v_add_f32_e32 v53, v50, v51
	v_frexp_mant_f32_e32 v50, v52
	v_cmp_gt_f32_e64 s[74:75], s25, v50
	v_cvt_f64_f32_e32 v[50:51], v52
	v_frexp_exp_i32_f64_e32 v50, v[50:51]
	v_subbrev_co_u32_e64 v58, s[74:75], 0, v50, s[74:75]
	v_sub_u32_e32 v50, 0, v58
	v_ldexp_f32 v51, v52, v50
	v_add_f32_e32 v52, -1.0, v51
	v_add_f32_e32 v54, 1.0, v51
	v_ldexp_f32 v50, v53, v50
	v_add_f32_e32 v53, 1.0, v52
	v_add_f32_e32 v55, -1.0, v54
	v_sub_f32_e32 v53, v51, v53
	v_sub_f32_e32 v51, v51, v55
	v_add_f32_e32 v53, v50, v53
	v_add_f32_e32 v50, v50, v51
	v_add_f32_e32 v59, v54, v50
	v_rcp_f32_e32 v61, v59
	v_sub_f32_e32 v51, v54, v59
	v_add_f32_e32 v60, v50, v51
	v_add_f32_e32 v51, v52, v53
	v_mul_f32_e32 v63, v51, v61
	v_sub_f32_e32 v50, v52, v51
	v_mul_f32_e32 v52, v59, v63
	v_fma_f32 v54, v63, v59, -v52
	v_fmac_f32_e32 v54, v63, v60
	v_add_f32_e32 v62, v53, v50
	v_add_f32_e32 v50, v52, v54
	v_sub_f32_e32 v53, v51, v50
	v_pk_add_f32 v[56:57], v[50:51], v[52:53] neg_lo:[0,1] neg_hi:[0,1]
	v_mov_b32_e32 v55, v50
	v_pk_add_f32 v[50:51], v[56:57], v[54:55] neg_lo:[0,1] neg_hi:[0,1]
	v_cmp_neq_f32_e64 s[74:75], s72, v67
	v_add_f32_e32 v51, v62, v51
	v_add_f32_e32 v50, v50, v51
	v_add_f32_e32 v51, v53, v50
	v_mul_f32_e32 v62, v61, v51
	v_mul_f32_e32 v52, v59, v62
	v_fma_f32 v54, v62, v59, -v52
	v_fmac_f32_e32 v54, v62, v60
	v_sub_f32_e32 v53, v53, v51
	v_add_f32_e32 v59, v50, v53
	v_add_f32_e32 v50, v52, v54
	v_sub_f32_e32 v53, v51, v50
	v_pk_add_f32 v[56:57], v[50:51], v[52:53] neg_lo:[0,1] neg_hi:[0,1]
	v_mov_b32_e32 v55, v50
	v_pk_add_f32 v[50:51], v[56:57], v[54:55] neg_lo:[0,1] neg_hi:[0,1]
	s_nop 0
	v_add_f32_e32 v51, v59, v51
	v_add_f32_e32 v50, v50, v51
	v_add_f32_e32 v51, v63, v62
	v_add_f32_e32 v50, v53, v50
	v_sub_f32_e32 v52, v51, v63
	v_mul_f32_e32 v50, v61, v50
	v_sub_f32_e32 v52, v62, v52
	v_add_f32_e32 v52, v52, v50
	v_add_f32_e32 v54, v51, v52
	v_mul_f32_e32 v55, v54, v54
	v_fmamk_f32 v50, v55, 0x3e9b6dac, v171
	v_fmaak_f32 v141, v55, v50, 0x3f2aaada
	v_cvt_f32_i32_e32 v50, v58
	v_sub_f32_e32 v51, v54, v51
	v_sub_f32_e32 v51, v52, v51
	v_ldexp_f32 v56, v51, 1
	v_mul_f32_e32 v51, v54, v55
	v_ldexp_f32 v53, v54, 1
	v_pk_mul_f32 v[54:55], v[50:51], v[140:141]
	s_nop 0
	v_fma_f32 v52, v50, s29, -v54
	v_fmac_f32_e32 v52, 0xb102e308, v50
	v_pk_add_f32 v[50:51], v[54:55], v[52:53]
	s_nop 0
	v_sub_f32_e32 v53, v51, v53
	v_sub_f32_e32 v53, v55, v53
	v_add_f32_e32 v57, v56, v53
	v_mov_b32_e32 v56, v54
	v_pk_add_f32 v[54:55], v[50:51], v[54:55] neg_lo:[0,1] neg_hi:[0,1]
	v_pk_add_f32 v[58:59], v[50:51], v[56:57]
	v_mov_b32_e32 v53, v50
	v_mov_b32_e32 v55, v59
	v_pk_add_f32 v[60:61], v[52:53], v[54:55] neg_lo:[0,1] neg_hi:[0,1]
	v_pk_add_f32 v[52:53], v[52:53], v[54:55]
	v_mov_b32_e32 v64, v51
	v_pk_add_f32 v[54:55], v[52:53], v[50:51] op_sel:[1,0] op_sel_hi:[0,1] neg_lo:[0,1] neg_hi:[0,1]
	v_pk_add_f32 v[62:63], v[58:59], v[54:55] op_sel_hi:[1,0] neg_lo:[0,1] neg_hi:[0,1]
	v_mov_b32_e32 v58, v59
	v_mov_b32_e32 v59, v53
	v_mov_b32_e32 v65, v54
	v_pk_add_f32 v[54:55], v[58:59], v[64:65] neg_lo:[0,1] neg_hi:[0,1]
	v_mov_b32_e32 v56, v57
	v_mov_b32_e32 v57, v50
	v_pk_add_f32 v[50:51], v[56:57], v[54:55] neg_lo:[0,1] neg_hi:[0,1]
	v_mov_b32_e32 v62, v60
	v_pk_add_f32 v[54:55], v[62:63], v[50:51]
	v_mov_b32_e32 v61, v53
	v_pk_add_f32 v[56:57], v[54:55], v[54:55] op_sel:[0,1] op_sel_hi:[1,0]
	s_nop 0
	v_pk_add_f32 v[52:53], v[52:53], v[56:57] op_sel:[1,0] op_sel_hi:[0,1]
	v_mov_b32_e32 v55, v52
	v_pk_add_f32 v[58:59], v[54:55], v[60:61] neg_lo:[0,1] neg_hi:[0,1]
	v_mov_b32_e32 v51, v56
	v_sub_f32_e32 v53, v54, v58
	v_pk_add_f32 v[50:51], v[50:51], v[58:59] neg_lo:[0,1] neg_hi:[0,1]
	v_sub_f32_e32 v53, v60, v53
	v_add_f32_e32 v50, v50, v53
	v_add_f32_e32 v50, v50, v51
	global_load_dword v51, v1, s[78:79] offset:32
	v_add_f32_e32 v50, v52, v50
	v_cndmask_b32_e64 v50, v182, v50, s[74:75]
	v_cmp_lt_f32_e64 s[74:75], |v67|, s73
	s_waitcnt vmcnt(0)
; #define LAS __attribute__((address_space(3)))
; __device__ __forceinline__ unsigned pk2(float lo, float hi) { const f32x2_t v = {lo, hi}; const bf16v2_t b = __builtin_convertvector(v, bf16v2_t); return __builtin_bit_cast(unsigned, b); }
; __device__ __forceinline__ float softplusf_(float x) { return fmaxf(x, 0.f) + log1pf(expf(-fabsf(x))); }
; __device__ __forceinline__ float log2_gamma(const Args& A, const Frame& F, int l, int dir, int h) {
;     const float x = GIN(12)[(l * 2 + dir) * NH + h];
;     return -softplusf_(-x) * 1.4426950408889634f;
; }
; __device__ __forceinline__ void ret_out_phase(const Args& A, Frame& F, int l, bool lastl, bf16_t* ARET, bf16_t* ALRU) {
;     ...
;         const float l2f = log2_gamma(A, F, l, 0, h), l2b = log2_gamma(A, F, l, 1, h);
;         bf16x8 pa[4];
;         {
;             const int i_loc = 16 * w + fr;
; #pragma unroll
;             for (int jp = 0; jp < 4; ++jp) {
;                 f32x4 c0 = (f32x4){0.f, 0.f, 0.f, 0.f}, c1 = c0;
; #pragma unroll
;                 for (int ks = 0; ks < 2; ++ks) {
;                     const bf16x8 k0 = *(const LAS bf16x8*)(ks_ + (32 * jp + fr) * 72 + 32 * ks + 8 * fq);
;                     const bf16x8 k1 = *(const LAS bf16x8*)(ks_ + (32 * jp + 16 + fr) * 72 + 32 * ks + 8 * fq);
;                     c0 = __builtin_amdgcn_mfma_f32_16x16x32_bf16(k0, qf[ks], c0, 0, 0, 0);
;                     c1 = __builtin_amdgcn_mfma_f32_16x16x32_bf16(k1, qf[ks], c1, 0, 0, 0);
;                 }
;                 float v[8];
; #pragma unroll
;                 for (int r = 0; r < 4; ++r) {
;                     const int j0 = 32 * jp + 4 * fq + r, j1 = j0 + 16;
;                     const int d0 = i_loc - j0, d1 = i_loc - j1;
;                     v[r] = c0[r] * (d0 >= 0 ? exp2f((float)d0 * l2f) : exp2f((float)(-d0) * l2b));
;                     v[4 + r] = c1[r] * (d1 >= 0 ? exp2f((float)d1 * l2f) : exp2f((float)(-d1) * l2b));
;                 }
;                 u32x4 pv; pv[0] = pk2(v[0], v[1]); pv[1] = pk2(v[2], v[3]); pv[2] = pk2(v[4], v[5]); pv[3] = pk2(v[6], v[7]);
;                 pa[jp] = __builtin_bit_cast(bf16x8, pv);
;             }
	v_mul_f32_e64 v52, |v51|, s59
	v_fma_f32 v53, |v51|, s59, -v52
	v_rndne_f32_e32 v54, v52
	v_fma_f32 v53, |v51|, s76, v53
	v_sub_f32_e32 v52, v52, v54
	v_add_f32_e32 v52, v52, v53
	v_exp_f32_e32 v52, v52
	v_cvt_i32_f32_e32 v53, v54
	v_cndmask_b32_e64 v50, v50, v67, s[74:75]
	v_cmp_ngt_f32_e64 s[74:75], |v51|, s77
	v_add_f32_e32 v50, v66, v50
	v_ldexp_f32 v52, v52, v53
	v_cndmask_b32_e64 v52, 0, v52, s[74:75]
	v_cmp_nlt_f32_e64 s[74:75], |v51|, s58
	v_mul_f32_e32 v66, 0xbfb8aa3b, v50
	v_max_f32_e64 v50, -v51, -v51
	v_cndmask_b32_e64 v51, v182, v52, s[74:75]
	v_add_f32_e32 v54, 1.0, v51
	v_add_f32_e32 v52, -1.0, v54
	v_sub_f32_e32 v53, v52, v54
	v_add_f32_e32 v53, 1.0, v53
	v_sub_f32_e32 v52, v51, v52
	v_add_f32_e32 v55, v52, v53
	v_frexp_mant_f32_e32 v52, v54
	v_cmp_gt_f32_e64 s[74:75], s25, v52
	v_cvt_f64_f32_e32 v[52:53], v54
	v_frexp_exp_i32_f64_e32 v52, v[52:53]
	v_subbrev_co_u32_e64 v52, s[74:75], 0, v52, s[74:75]
	v_sub_u32_e32 v53, 0, v52
	v_ldexp_f32 v54, v54, v53
	v_add_f32_e32 v56, -1.0, v54
	v_ldexp_f32 v53, v55, v53
	v_add_f32_e32 v55, 1.0, v56
	v_sub_f32_e32 v55, v54, v55
	v_add_f32_e32 v57, v53, v55
	v_add_f32_e32 v55, 1.0, v54
	v_add_f32_e32 v58, -1.0, v55
	v_sub_f32_e32 v54, v54, v58
	v_add_f32_e32 v53, v53, v54
	v_add_f32_e32 v62, v55, v53
	v_rcp_f32_e32 v63, v62
	v_sub_f32_e32 v54, v55, v62
	v_add_f32_e32 v55, v56, v57
	v_add_f32_e32 v53, v53, v54
	v_mul_f32_e32 v65, v55, v63
	v_sub_f32_e32 v54, v56, v55
	v_mul_f32_e32 v56, v62, v65
	v_fma_f32 v58, v65, v62, -v56
	v_fmac_f32_e32 v58, v65, v53
	v_add_f32_e32 v64, v57, v54
	v_add_f32_e32 v54, v56, v58
	v_sub_f32_e32 v57, v55, v54
	v_pk_add_f32 v[60:61], v[54:55], v[56:57] neg_lo:[0,1] neg_hi:[0,1]
	v_mov_b32_e32 v59, v54
	v_pk_add_f32 v[54:55], v[60:61], v[58:59] neg_lo:[0,1] neg_hi:[0,1]
	v_cvt_f32_i32_e32 v52, v52
	v_add_f32_e32 v55, v64, v55
	v_add_f32_e32 v54, v54, v55
	v_add_f32_e32 v55, v57, v54
	v_mul_f32_e32 v64, v63, v55
	v_mul_f32_e32 v56, v62, v64
	v_fma_f32 v58, v64, v62, -v56
	v_fmac_f32_e32 v58, v64, v53
	v_sub_f32_e32 v53, v57, v55
	v_add_f32_e32 v53, v54, v53
	v_add_f32_e32 v54, v56, v58
	v_sub_f32_e32 v57, v55, v54
	v_pk_add_f32 v[60:61], v[54:55], v[56:57] neg_lo:[0,1] neg_hi:[0,1]
	v_mov_b32_e32 v59, v54
	v_pk_add_f32 v[54:55], v[60:61], v[58:59] neg_lo:[0,1] neg_hi:[0,1]
	v_cmp_neq_f32_e64 s[74:75], s72, v51
	v_add_f32_e32 v53, v53, v55
	v_add_f32_e32 v53, v54, v53
	v_add_f32_e32 v54, v65, v64
	v_add_f32_e32 v53, v57, v53
	v_sub_f32_e32 v55, v54, v65
	v_mul_f32_e32 v53, v63, v53
	v_sub_f32_e32 v55, v64, v55
	v_add_f32_e32 v53, v55, v53
	v_add_f32_e32 v56, v54, v53
	v_mul_f32_e32 v57, v56, v56
	v_sub_f32_e32 v54, v56, v54
	v_fmamk_f32 v55, v57, 0x3e9b6dac, v171
	v_sub_f32_e32 v53, v53, v54
	v_fmaak_f32 v141, v57, v55, 0x3f2aaada
	v_ldexp_f32 v58, v53, 1
	v_mul_f32_e32 v53, v56, v57
	v_ldexp_f32 v55, v56, 1
	v_pk_mul_f32 v[56:57], v[52:53], v[140:141]
	v_max_f32_e32 v50, 0, v50
	v_fma_f32 v54, v52, s29, -v56
	v_fmac_f32_e32 v54, 0xb102e308, v52
	v_pk_add_f32 v[52:53], v[56:57], v[54:55]
	s_nop 0
	v_sub_f32_e32 v55, v53, v55
	v_sub_f32_e32 v55, v57, v55
	v_add_f32_e32 v59, v58, v55
	v_mov_b32_e32 v58, v56
	v_pk_add_f32 v[56:57], v[52:53], v[56:57] neg_lo:[0,1] neg_hi:[0,1]
	v_pk_add_f32 v[60:61], v[52:53], v[58:59]
	v_mov_b32_e32 v55, v52
	v_mov_b32_e32 v57, v61
	v_pk_add_f32 v[62:63], v[54:55], v[56:57] neg_lo:[0,1] neg_hi:[0,1]
	v_pk_add_f32 v[54:55], v[54:55], v[56:57]
	v_mov_b32_e32 v68, v53
	v_pk_add_f32 v[56:57], v[54:55], v[52:53] op_sel:[1,0] op_sel_hi:[0,1] neg_lo:[0,1] neg_hi:[0,1]
	v_pk_add_f32 v[64:65], v[60:61], v[56:57] op_sel_hi:[1,0] neg_lo:[0,1] neg_hi:[0,1]
	v_mov_b32_e32 v60, v61
	v_mov_b32_e32 v61, v55
	v_mov_b32_e32 v69, v56
	v_pk_add_f32 v[56:57], v[60:61], v[68:69] neg_lo:[0,1] neg_hi:[0,1]
	v_mov_b32_e32 v58, v59
	v_mov_b32_e32 v59, v52
	v_pk_add_f32 v[52:53], v[58:59], v[56:57] neg_lo:[0,1] neg_hi:[0,1]
	v_mov_b32_e32 v64, v62
	v_pk_add_f32 v[56:57], v[64:65], v[52:53]
	v_mov_b32_e32 v63, v55
	v_pk_add_f32 v[58:59], v[56:57], v[56:57] op_sel:[0,1] op_sel_hi:[1,0]
	s_nop 0
	v_pk_add_f32 v[54:55], v[54:55], v[58:59] op_sel:[1,0] op_sel_hi:[0,1]
	v_mov_b32_e32 v57, v54
	v_pk_add_f32 v[60:61], v[56:57], v[62:63] neg_lo:[0,1] neg_hi:[0,1]
	v_mov_b32_e32 v53, v58
	v_sub_f32_e32 v55, v56, v60
	v_pk_add_f32 v[52:53], v[52:53], v[60:61] neg_lo:[0,1] neg_hi:[0,1]
	v_sub_f32_e32 v55, v62, v55
	v_add_f32_e32 v52, v52, v55
	v_add_f32_e32 v52, v52, v53
	v_add_f32_e32 v52, v54, v52
	v_cndmask_b32_e64 v52, v182, v52, s[74:75]
	v_cmp_lt_f32_e64 s[74:75], |v51|, s73
	s_nop 1
	v_cndmask_b32_e64 v51, v52, v51, s[74:75]
	v_add_f32_e32 v50, v50, v51
	v_mul_f32_e32 v67, 0xbfb8aa3b, v50
	ds_read_b128 v[50:53], v143
	ds_read_b128 v[54:57], v143 offset:2304
	s_waitcnt lgkmcnt(1)
	v_mfma_f32_16x16x32_bf16 v[50:53], v[50:53], v[46:49], 0
	ds_read_b128 v[58:61], v143 offset:64
	ds_read_b128 v[62:65], v143 offset:2368
	s_waitcnt lgkmcnt(1)
	v_mfma_f32_16x16x32_bf16 v[50:53], v[58:61], v[42:45], v[50:53]
	v_mul_f32_e32 v58, v67, v144
	v_mul_f32_e32 v59, v66, v145
	v_cndmask_b32_e64 v58, v59, v58, s[4:5]
	v_cmp_gt_f32_e64 s[74:75], s3, v58
	v_readlane_b32 s4, v254, 36
	v_mul_f32_e32 v60, v66, v147
	v_cndmask_b32_e64 v59, 0, v183, s[74:75]
	v_add_f32_e32 v58, v58, v59
	v_exp_f32_e32 v58, v58
	v_cndmask_b32_e64 v59, 0, v184, s[74:75]
	v_readlane_b32 s5, v254, 37
	v_mul_f32_e32 v61, v67, v148
	v_ldexp_f32 v58, v58, v59
	v_mul_f32_e32 v59, v67, v146
	v_cndmask_b32_e64 v59, v60, v59, s[4:5]
	v_cmp_gt_f32_e64 s[74:75], s3, v59
	v_readlane_b32 s4, v254, 40
	v_readlane_b32 s5, v254, 41
	v_cndmask_b32_e64 v60, 0, v183, s[74:75]
	v_add_f32_e32 v59, v59, v60
	v_exp_f32_e32 v59, v59
	v_cndmask_b32_e64 v60, 0, v184, s[74:75]
	v_mfma_f32_16x16x32_bf16 v[54:57], v[54:57], v[46:49], 0
	v_ldexp_f32 v60, v59, v60
	v_mul_f32_e32 v59, v66, v149
	v_cndmask_b32_e64 v59, v59, v61, s[4:5]
	v_cmp_gt_f32_e64 s[74:75], s3, v59
	v_readlane_b32 s4, v254, 42
	v_readlane_b32 s5, v254, 43
	v_cndmask_b32_e64 v61, 0, v183, s[74:75]
	v_add_f32_e32 v59, v59, v61
	v_exp_f32_e32 v59, v59
	v_cndmask_b32_e64 v61, 0, v184, s[74:75]
	s_waitcnt lgkmcnt(0)
; #define LAS __attribute__((address_space(3)))
; __device__ __forceinline__ unsigned pk2(float lo, float hi) { const f32x2_t v = {lo, hi}; const bf16v2_t b = __builtin_convertvector(v, bf16v2_t); return __builtin_bit_cast(unsigned, b); }
; __device__ __forceinline__ void ret_out_phase(const Args& A, Frame& F, int l, bool lastl, bf16_t* ARET, bf16_t* ALRU) {
;     ...
;             for (int jp = 0; jp < 4; ++jp) {
;                 f32x4 c0 = (f32x4){0.f, 0.f, 0.f, 0.f}, c1 = c0;
; #pragma unroll
;                 for (int ks = 0; ks < 2; ++ks) {
;                     const bf16x8 k0 = *(const LAS bf16x8*)(ks_ + (32 * jp + fr) * 72 + 32 * ks + 8 * fq);
;                     const bf16x8 k1 = *(const LAS bf16x8*)(ks_ + (32 * jp + 16 + fr) * 72 + 32 * ks + 8 * fq);
;                     c0 = __builtin_amdgcn_mfma_f32_16x16x32_bf16(k0, qf[ks], c0, 0, 0, 0);
;                     c1 = __builtin_amdgcn_mfma_f32_16x16x32_bf16(k1, qf[ks], c1, 0, 0, 0);
;                 }
;                 float v[8];
; #pragma unroll
;                 for (int r = 0; r < 4; ++r) {
;                     const int j0 = 32 * jp + 4 * fq + r, j1 = j0 + 16;
;                     const int d0 = i_loc - j0, d1 = i_loc - j1;
;                     v[r] = c0[r] * (d0 >= 0 ? exp2f((float)d0 * l2f) : exp2f((float)(-d0) * l2b));
;                     v[4 + r] = c1[r] * (d1 >= 0 ? exp2f((float)d1 * l2f) : exp2f((float)(-d1) * l2b));
;                 }
;                 u32x4 pv; pv[0] = pk2(v[0], v[1]); pv[1] = pk2(v[2], v[3]); pv[2] = pk2(v[4], v[5]); pv[3] = pk2(v[6], v[7]);
;                 pa[jp] = __builtin_bit_cast(bf16x8, pv);
;             }
	v_mfma_f32_16x16x32_bf16 v[54:57], v[62:65], v[42:45], v[54:57]
	v_ldexp_f32 v59, v59, v61
	v_pk_mul_f32 v[50:51], v[50:51], v[58:59]
	v_mul_f32_e32 v58, v66, v151
	v_mul_f32_e32 v59, v67, v150
	v_cndmask_b32_e64 v58, v58, v59, s[4:5]
	v_cmp_gt_f32_e64 s[74:75], s3, v58
	v_readlane_b32 s4, v254, 44
	v_readlane_b32 s5, v254, 45
	v_cndmask_b32_e64 v59, 0, v183, s[74:75]
	v_add_f32_e32 v58, v58, v59
	v_exp_f32_e32 v58, v58
	v_cndmask_b32_e64 v59, 0, v184, s[74:75]
	v_cvt_pk_bf16_f32 v50, v50, v51
	v_ldexp_f32 v61, v58, v59
	v_mul_f32_e32 v58, v66, v153
	v_mul_f32_e32 v59, v67, v152
	v_cndmask_b32_e64 v58, v58, v59, s[4:5]
	v_cmp_gt_f32_e64 s[74:75], s3, v58
	v_readlane_b32 s4, v254, 46
	v_pk_mul_f32 v[54:55], v[54:55], v[60:61]
	v_cndmask_b32_e64 v59, 0, v183, s[74:75]
	v_add_f32_e32 v58, v58, v59
	v_exp_f32_e32 v58, v58
	v_cndmask_b32_e64 v59, 0, v184, s[74:75]
	v_mul_f32_e32 v60, v67, v154
	v_readlane_b32 s5, v254, 47
	v_ldexp_f32 v58, v58, v59
	v_mul_f32_e32 v59, v66, v155
	v_cndmask_b32_e64 v59, v59, v60, s[4:5]
	v_cmp_gt_f32_e64 s[74:75], s3, v59
	v_readlane_b32 s4, v254, 48
	v_mul_f32_e32 v61, v67, v156
	v_cndmask_b32_e64 v60, 0, v183, s[74:75]
	v_add_f32_e32 v59, v59, v60
	v_exp_f32_e32 v59, v59
	v_cndmask_b32_e64 v60, 0, v184, s[74:75]
	v_readlane_b32 s5, v254, 49
	v_ldexp_f32 v60, v59, v60
	v_mul_f32_e32 v59, v66, v157
	v_cndmask_b32_e64 v59, v59, v61, s[4:5]
	v_cmp_gt_f32_e64 s[74:75], s3, v59
	v_readlane_b32 s4, v254, 50
	v_readlane_b32 s5, v254, 51
	v_cndmask_b32_e64 v61, 0, v183, s[74:75]
	v_add_f32_e32 v59, v59, v61
	v_exp_f32_e32 v59, v59
	v_cndmask_b32_e64 v61, 0, v184, s[74:75]
	v_ldexp_f32 v59, v59, v61
	v_pk_mul_f32 v[52:53], v[52:53], v[58:59]
	v_mul_f32_e32 v58, v66, v159
	v_mul_f32_e32 v59, v67, v158
	v_cndmask_b32_e64 v58, v58, v59, s[4:5]
	v_cmp_gt_f32_e64 s[74:75], s3, v58
	v_cvt_pk_bf16_f32 v51, v52, v53
	v_cvt_pk_bf16_f32 v52, v54, v55
	v_cndmask_b32_e64 v59, 0, v183, s[74:75]
	v_add_f32_e32 v58, v58, v59
	v_exp_f32_e32 v58, v58
	v_cndmask_b32_e64 v59, 0, v184, s[74:75]
	v_readlane_b32 s4, v254, 52
	v_readlane_b32 s5, v254, 53
	v_ldexp_f32 v61, v58, v59
	v_pk_mul_f32 v[56:57], v[56:57], v[60:61]
	s_nop 0
	v_cvt_pk_bf16_f32 v53, v56, v57
	ds_read_b128 v[54:57], v160
	ds_read_b128 v[58:61], v160 offset:2304
	s_waitcnt lgkmcnt(1)
	v_mfma_f32_16x16x32_bf16 v[54:57], v[54:57], v[46:49], 0
	ds_read_b128 v[62:65], v160 offset:64
	ds_read_b128 v[68:71], v160 offset:2368
	s_waitcnt lgkmcnt(1)
	v_mfma_f32_16x16x32_bf16 v[54:57], v[62:65], v[42:45], v[54:57]
	v_mul_f32_e32 v62, v66, v162
	v_mul_f32_e32 v63, v67, v161
	v_cndmask_b32_e64 v62, v62, v63, s[4:5]
	v_cmp_gt_f32_e64 s[74:75], s3, v62
	v_readlane_b32 s4, v254, 54
	v_mul_f32_e32 v64, v67, v163
	v_cndmask_b32_e64 v63, 0, v183, s[74:75]
	v_add_f32_e32 v62, v62, v63
	v_exp_f32_e32 v62, v62
	v_cndmask_b32_e64 v63, 0, v184, s[74:75]
	v_readlane_b32 s5, v254, 55
	v_mul_f32_e32 v65, v67, v165
	v_ldexp_f32 v62, v62, v63
	v_mul_f32_e32 v63, v66, v164
	v_cndmask_b32_e64 v63, v63, v64, s[4:5]
	v_cmp_gt_f32_e64 s[74:75], s3, v63
	v_readlane_b32 s4, v254, 56
	v_readlane_b32 s5, v254, 57
	v_cndmask_b32_e64 v64, 0, v183, s[74:75]
	v_add_f32_e32 v63, v63, v64
	v_exp_f32_e32 v63, v63
	v_cndmask_b32_e64 v64, 0, v184, s[74:75]
	v_mfma_f32_16x16x32_bf16 v[58:61], v[58:61], v[46:49], 0
	v_ldexp_f32 v64, v63, v64
	v_mul_f32_e32 v63, v66, v166
	v_cndmask_b32_e64 v63, v63, v65, s[4:5]
	v_cmp_gt_f32_e64 s[74:75], s3, v63
	v_readlane_b32 s4, v254, 58
	v_readlane_b32 s5, v254, 59
	v_cndmask_b32_e64 v65, 0, v183, s[74:75]
	v_add_f32_e32 v63, v63, v65
	v_exp_f32_e32 v63, v63
	v_cndmask_b32_e64 v65, 0, v184, s[74:75]
	s_waitcnt lgkmcnt(0)
	v_mfma_f32_16x16x32_bf16 v[58:61], v[68:71], v[42:45], v[58:61]
	v_ldexp_f32 v63, v63, v65
	v_pk_mul_f32 v[54:55], v[54:55], v[62:63]
	v_mul_f32_e32 v62, v66, v168
	v_mul_f32_e32 v63, v67, v167
	v_cndmask_b32_e64 v62, v62, v63, s[4:5]
	v_cmp_gt_f32_e64 s[74:75], s3, v62
	v_readlane_b32 s4, v254, 60
	v_readlane_b32 s5, v254, 61
	v_cndmask_b32_e64 v63, 0, v183, s[74:75]
	v_add_f32_e32 v62, v62, v63
	v_exp_f32_e32 v62, v62
	v_cndmask_b32_e64 v63, 0, v184, s[74:75]
	v_cvt_pk_bf16_f32 v54, v54, v55
	v_ldexp_f32 v65, v62, v63
	v_mul_f32_e32 v62, v66, v189
	v_mul_f32_e32 v63, v67, v169
	v_cndmask_b32_e64 v62, v62, v63, s[4:5]
	v_cmp_gt_f32_e64 s[74:75], s3, v62
	v_readlane_b32 s4, v254, 62
	v_pk_mul_f32 v[58:59], v[58:59], v[64:65]
	v_cndmask_b32_e64 v63, 0, v183, s[74:75]
	v_add_f32_e32 v62, v62, v63
	v_exp_f32_e32 v62, v62
	v_cndmask_b32_e64 v63, 0, v184, s[74:75]
	v_mul_f32_e32 v64, v67, v190
	v_readlane_b32 s5, v254, 63
	v_ldexp_f32 v62, v62, v63
	v_mul_f32_e32 v63, v66, v191
	v_cndmask_b32_e64 v63, v63, v64, s[4:5]
	v_cmp_gt_f32_e64 s[74:75], s3, v63
	v_readlane_b32 s4, v255, 0
	v_mul_f32_e32 v65, v67, v192
	v_cndmask_b32_e64 v64, 0, v183, s[74:75]
	v_add_f32_e32 v63, v63, v64
	v_exp_f32_e32 v63, v63
	v_cndmask_b32_e64 v64, 0, v184, s[74:75]
	v_readlane_b32 s5, v255, 1
	v_ldexp_f32 v64, v63, v64
	v_mul_f32_e32 v63, v66, v193
	v_cndmask_b32_e64 v63, v63, v65, s[4:5]
	v_cmp_gt_f32_e64 s[74:75], s3, v63
	v_readlane_b32 s4, v255, 2
	v_readlane_b32 s5, v255, 3
	v_cndmask_b32_e64 v65, 0, v183, s[74:75]
	v_add_f32_e32 v63, v63, v65
	v_exp_f32_e32 v63, v63
	v_cndmask_b32_e64 v65, 0, v184, s[74:75]
	v_ldexp_f32 v63, v63, v65
	v_pk_mul_f32 v[56:57], v[56:57], v[62:63]
	v_mul_f32_e32 v62, v66, v195
	v_mul_f32_e32 v63, v67, v194
	v_cndmask_b32_e64 v62, v62, v63, s[4:5]
	v_cmp_gt_f32_e64 s[74:75], s3, v62
	v_cvt_pk_bf16_f32 v55, v56, v57
	v_cvt_pk_bf16_f32 v56, v58, v59
	v_cndmask_b32_e64 v63, 0, v183, s[74:75]
	v_add_f32_e32 v62, v62, v63
	v_exp_f32_e32 v62, v62
	v_cndmask_b32_e64 v63, 0, v184, s[74:75]
	v_readlane_b32 s4, v255, 4
	v_readlane_b32 s5, v255, 5
	v_ldexp_f32 v65, v62, v63
	v_pk_mul_f32 v[60:61], v[60:61], v[64:65]
	s_nop 0
	v_cvt_pk_bf16_f32 v57, v60, v61
	ds_read_b128 v[58:61], v196
	ds_read_b128 v[62:65], v196 offset:2304
	s_waitcnt lgkmcnt(1)
; #define LAS __attribute__((address_space(3)))
; __device__ __forceinline__ unsigned pk2(float lo, float hi) { const f32x2_t v = {lo, hi}; const bf16v2_t b = __builtin_convertvector(v, bf16v2_t); return __builtin_bit_cast(unsigned, b); }
; __device__ __forceinline__ void ret_out_phase(const Args& A, Frame& F, int l, bool lastl, bf16_t* ARET, bf16_t* ALRU) {
;     ...
;             for (int jp = 0; jp < 4; ++jp) {
;                 f32x4 c0 = (f32x4){0.f, 0.f, 0.f, 0.f}, c1 = c0;
; #pragma unroll
;                 for (int ks = 0; ks < 2; ++ks) {
;                     const bf16x8 k0 = *(const LAS bf16x8*)(ks_ + (32 * jp + fr) * 72 + 32 * ks + 8 * fq);
;                     const bf16x8 k1 = *(const LAS bf16x8*)(ks_ + (32 * jp + 16 + fr) * 72 + 32 * ks + 8 * fq);
;                     c0 = __builtin_amdgcn_mfma_f32_16x16x32_bf16(k0, qf[ks], c0, 0, 0, 0);
;                     c1 = __builtin_amdgcn_mfma_f32_16x16x32_bf16(k1, qf[ks], c1, 0, 0, 0);
;                 }
;                 float v[8];
; #pragma unroll
;                 for (int r = 0; r < 4; ++r) {
;                     const int j0 = 32 * jp + 4 * fq + r, j1 = j0 + 16;
;                     const int d0 = i_loc - j0, d1 = i_loc - j1;
;                     v[r] = c0[r] * (d0 >= 0 ? exp2f((float)d0 * l2f) : exp2f((float)(-d0) * l2b));
;                     v[4 + r] = c1[r] * (d1 >= 0 ? exp2f((float)d1 * l2f) : exp2f((float)(-d1) * l2b));
;                 }
;                 u32x4 pv; pv[0] = pk2(v[0], v[1]); pv[1] = pk2(v[2], v[3]); pv[2] = pk2(v[4], v[5]); pv[3] = pk2(v[6], v[7]);
;                 pa[jp] = __builtin_bit_cast(bf16x8, pv);
;             }
	v_mfma_f32_16x16x32_bf16 v[58:61], v[58:61], v[46:49], 0
	ds_read_b128 v[68:71], v196 offset:64
	ds_read_b128 v[72:75], v196 offset:2368
	s_waitcnt lgkmcnt(1)
	v_mfma_f32_16x16x32_bf16 v[58:61], v[68:71], v[42:45], v[58:61]
	v_mul_f32_e32 v68, v66, v198
	v_mul_f32_e32 v69, v67, v197
	v_cndmask_b32_e64 v68, v68, v69, s[4:5]
	v_cmp_gt_f32_e64 s[74:75], s3, v68
	v_readlane_b32 s4, v255, 6
	v_mul_f32_e32 v70, v67, v199
	v_cndmask_b32_e64 v69, 0, v183, s[74:75]
	v_add_f32_e32 v68, v68, v69
	v_exp_f32_e32 v68, v68
	v_cndmask_b32_e64 v69, 0, v184, s[74:75]
	v_readlane_b32 s5, v255, 7
	v_mul_f32_e32 v71, v67, v201
	v_ldexp_f32 v68, v68, v69
	v_mul_f32_e32 v69, v66, v200
	v_cndmask_b32_e64 v69, v69, v70, s[4:5]
	v_cmp_gt_f32_e64 s[74:75], s3, v69
	v_readlane_b32 s4, v255, 8
	v_readlane_b32 s5, v255, 9
	v_cndmask_b32_e64 v70, 0, v183, s[74:75]
	v_add_f32_e32 v69, v69, v70
	v_exp_f32_e32 v69, v69
	v_cndmask_b32_e64 v70, 0, v184, s[74:75]
	v_mfma_f32_16x16x32_bf16 v[62:65], v[62:65], v[46:49], 0
	v_ldexp_f32 v70, v69, v70
	v_mul_f32_e32 v69, v66, v202
	v_cndmask_b32_e64 v69, v69, v71, s[4:5]
	v_cmp_gt_f32_e64 s[74:75], s3, v69
	v_readlane_b32 s4, v255, 10
	v_readlane_b32 s5, v255, 11
	v_cndmask_b32_e64 v71, 0, v183, s[74:75]
	v_add_f32_e32 v69, v69, v71
	v_exp_f32_e32 v69, v69
	v_cndmask_b32_e64 v71, 0, v184, s[74:75]
	s_waitcnt lgkmcnt(0)
	v_mfma_f32_16x16x32_bf16 v[62:65], v[72:75], v[42:45], v[62:65]
	v_ldexp_f32 v69, v69, v71
	v_pk_mul_f32 v[58:59], v[58:59], v[68:69]
	v_mul_f32_e32 v68, v66, v204
	v_mul_f32_e32 v69, v67, v203
	v_cndmask_b32_e64 v68, v68, v69, s[4:5]
	v_cmp_gt_f32_e64 s[74:75], s3, v68
	v_readlane_b32 s4, v255, 12
	v_readlane_b32 s5, v255, 13
	v_cndmask_b32_e64 v69, 0, v183, s[74:75]
	v_add_f32_e32 v68, v68, v69
	v_exp_f32_e32 v68, v68
	v_cndmask_b32_e64 v69, 0, v184, s[74:75]
	v_cvt_pk_bf16_f32 v58, v58, v59
	v_ldexp_f32 v71, v68, v69
	v_mul_f32_e32 v68, v66, v206
	v_mul_f32_e32 v69, v67, v205
	v_cndmask_b32_e64 v68, v68, v69, s[4:5]
	v_cmp_gt_f32_e64 s[74:75], s3, v68
	v_readlane_b32 s4, v255, 14
	v_pk_mul_f32 v[62:63], v[62:63], v[70:71]
	v_cndmask_b32_e64 v69, 0, v183, s[74:75]
	v_add_f32_e32 v68, v68, v69
	v_exp_f32_e32 v68, v68
	v_cndmask_b32_e64 v69, 0, v184, s[74:75]
	v_mul_f32_e32 v70, v67, v207
	v_readlane_b32 s5, v255, 15
	v_ldexp_f32 v68, v68, v69
	v_mul_f32_e32 v69, v66, v208
	v_cndmask_b32_e64 v69, v69, v70, s[4:5]
	v_cmp_gt_f32_e64 s[74:75], s3, v69
	v_readlane_b32 s4, v255, 16
	v_mul_f32_e32 v71, v67, v209
	v_cndmask_b32_e64 v70, 0, v183, s[74:75]
	v_add_f32_e32 v69, v69, v70
	v_exp_f32_e32 v69, v69
	v_cndmask_b32_e64 v70, 0, v184, s[74:75]
	v_readlane_b32 s5, v255, 17
	v_ldexp_f32 v70, v69, v70
	v_mul_f32_e32 v69, v66, v210
	v_cndmask_b32_e64 v69, v69, v71, s[4:5]
	v_cmp_gt_f32_e64 s[74:75], s3, v69
	v_readlane_b32 s4, v255, 18
	v_readlane_b32 s5, v255, 19
	v_cndmask_b32_e64 v71, 0, v183, s[74:75]
	v_add_f32_e32 v69, v69, v71
	v_exp_f32_e32 v69, v69
	v_cndmask_b32_e64 v71, 0, v184, s[74:75]
	v_ldexp_f32 v69, v69, v71
	v_pk_mul_f32 v[60:61], v[60:61], v[68:69]
	v_mul_f32_e32 v68, v66, v212
	v_mul_f32_e32 v69, v67, v211
	v_cndmask_b32_e64 v68, v68, v69, s[4:5]
	v_cmp_gt_f32_e64 s[74:75], s3, v68
	v_cvt_pk_bf16_f32 v59, v60, v61
	v_cvt_pk_bf16_f32 v60, v62, v63
	v_cndmask_b32_e64 v69, 0, v183, s[74:75]
	v_add_f32_e32 v68, v68, v69
	v_exp_f32_e32 v68, v68
	v_cndmask_b32_e64 v69, 0, v184, s[74:75]
	v_readlane_b32 s4, v255, 20
	v_readlane_b32 s5, v255, 21
	v_ldexp_f32 v71, v68, v69
	v_pk_mul_f32 v[64:65], v[64:65], v[70:71]
	s_nop 0
	v_cvt_pk_bf16_f32 v61, v64, v65
	ds_read_b128 v[62:65], v213
	ds_read_b128 v[68:71], v213 offset:2304
	s_waitcnt lgkmcnt(1)
	v_mfma_f32_16x16x32_bf16 v[62:65], v[62:65], v[46:49], 0
	ds_read_b128 v[72:75], v213 offset:64
	ds_read_b128 v[76:79], v213 offset:2368
	s_waitcnt lgkmcnt(1)
	v_mfma_f32_16x16x32_bf16 v[62:65], v[72:75], v[42:45], v[62:65]
	v_mul_f32_e32 v72, v66, v215
	v_mul_f32_e32 v73, v67, v214
	v_cndmask_b32_e64 v72, v72, v73, s[4:5]
	v_cmp_gt_f32_e64 s[74:75], s3, v72
	v_readlane_b32 s4, v255, 22
	v_mul_f32_e32 v74, v67, v216
	v_cndmask_b32_e64 v73, 0, v183, s[74:75]
	v_add_f32_e32 v72, v72, v73
	v_exp_f32_e32 v72, v72
	v_cndmask_b32_e64 v73, 0, v184, s[74:75]
	v_readlane_b32 s5, v255, 23
	v_mul_f32_e32 v75, v67, v218
	v_ldexp_f32 v72, v72, v73
	v_mul_f32_e32 v73, v66, v217
	v_cndmask_b32_e64 v73, v73, v74, s[4:5]
	v_cmp_gt_f32_e64 s[74:75], s3, v73
	v_readlane_b32 s4, v255, 24
	v_readlane_b32 s5, v255, 25
	v_cndmask_b32_e64 v74, 0, v183, s[74:75]
	v_add_f32_e32 v73, v73, v74
	v_exp_f32_e32 v73, v73
	v_cndmask_b32_e64 v74, 0, v184, s[74:75]
	v_mfma_f32_16x16x32_bf16 v[68:71], v[68:71], v[46:49], 0
	v_ldexp_f32 v74, v73, v74
	v_mul_f32_e32 v73, v66, v219
	v_cndmask_b32_e64 v73, v73, v75, s[4:5]
	v_cmp_gt_f32_e64 s[74:75], s3, v73
	v_readlane_b32 s4, v255, 26
	v_readlane_b32 s5, v255, 27
	v_cndmask_b32_e64 v75, 0, v183, s[74:75]
	v_add_f32_e32 v73, v73, v75
	v_exp_f32_e32 v73, v73
	v_cndmask_b32_e64 v75, 0, v184, s[74:75]
	s_waitcnt lgkmcnt(0)
; #define LAS __attribute__((address_space(3)))
; __device__ __forceinline__ unsigned pk2(float lo, float hi) { const f32x2_t v = {lo, hi}; const bf16v2_t b = __builtin_convertvector(v, bf16v2_t); return __builtin_bit_cast(unsigned, b); }
; __device__ __forceinline__ void ret_out_phase(const Args& A, Frame& F, int l, bool lastl, bf16_t* ARET, bf16_t* ALRU) {
;     ...
;                     const int d0 = i_loc - j0, d1 = i_loc - j1;
;                     v[r] = c0[r] * (d0 >= 0 ? exp2f((float)d0 * l2f) : exp2f((float)(-d0) * l2b));
;                     v[4 + r] = c1[r] * (d1 >= 0 ? exp2f((float)d1 * l2f) : exp2f((float)(-d1) * l2b));
;                 }
;                 u32x4 pv; pv[0] = pk2(v[0], v[1]); pv[1] = pk2(v[2], v[3]); pv[2] = pk2(v[4], v[5]); pv[3] = pk2(v[6], v[7]);
;                 pa[jp] = __builtin_bit_cast(bf16x8, pv);
;             }
;         }
;         bf16x8 qF[2], qB[2];
;         {
;             const int il = 16 * w + fr;
;             const float sF = exp2f((float)(il + 1) * l2f), sB = exp2f((float)(128 - il) * l2b);
; #pragma unroll
;             for (int ks = 0; ks < 2; ++ks) { qF[ks] = scale1(qf[ks], sF); qB[ks] = scale1(qf[ks], sB); }
;         }
;         f32x4 O[8];
; #pragma unroll
;         for (int dvt = 0; dvt < 8; ++dvt) {
;             f32x4 o = (f32x4){0.f, 0.f, 0.f, 0.f};
; #pragma unroll
;             for (int jp = 0; jp < 4; ++jp) {
;                 const u32x2 lo = *(const LAS u32x2*)(vts + (16 * dvt + fr) * 136 + 32 * jp + 4 * fq);
;                 const u32x2 hi = *(const LAS u32x2*)(vts + (16 * dvt + fr) * 136 + 32 * jp + 16 + 4 * fq);
;                 u32x4 bv; bv[0] = lo.x; bv[1] = lo.y; bv[2] = hi.x; bv[3] = hi.y;
;                 o = __builtin_amdgcn_mfma_f32_16x16x32_bf16(pa[jp], __builtin_bit_cast(bf16x8, bv), o, 0, 0, 0);
;             }
; #pragma unroll
;             for (int ks = 0; ks < 2; ++ks) {
;                 const bf16x8 sf = *(const LAS bf16x8*)(sfs + (16 * dvt + fr) * 72 + 32 * ks + 8 * fq);
;                 const bf16x8 sb = *(const LAS bf16x8*)(sbs + (16 * dvt + fr) * 72 + 32 * ks + 8 * fq);
;                 o = __builtin_amdgcn_mfma_f32_16x16x32_bf16(qF[ks], sf, o, 0, 0, 0);
;                 o = __builtin_amdgcn_mfma_f32_16x16x32_bf16(qB[ks], sb, o, 0, 0, 0);
;             }
	v_mfma_f32_16x16x32_bf16 v[68:71], v[76:79], v[42:45], v[68:71]
	v_ldexp_f32 v73, v73, v75
	v_pk_mul_f32 v[62:63], v[62:63], v[72:73]
	v_mul_f32_e32 v72, v66, v221
	v_mul_f32_e32 v73, v67, v220
	v_cndmask_b32_e64 v72, v72, v73, s[4:5]
	v_cmp_gt_f32_e64 s[74:75], s3, v72
	v_readlane_b32 s4, v255, 28
	v_readlane_b32 s5, v255, 29
	v_cndmask_b32_e64 v73, 0, v183, s[74:75]
	v_add_f32_e32 v72, v72, v73
	v_exp_f32_e32 v72, v72
	v_cndmask_b32_e64 v73, 0, v184, s[74:75]
	v_cvt_pk_bf16_f32 v62, v62, v63
	v_ldexp_f32 v75, v72, v73
	v_mul_f32_e32 v72, v66, v223
	v_mul_f32_e32 v73, v67, v222
	v_cndmask_b32_e64 v72, v72, v73, s[4:5]
	v_cmp_gt_f32_e64 s[74:75], s3, v72
	v_pk_mul_f32 v[68:69], v[68:69], v[74:75]
	v_mul_f32_e32 v74, v67, v224
	v_cndmask_b32_e64 v73, 0, v183, s[74:75]
	v_add_f32_e32 v72, v72, v73
	v_exp_f32_e32 v72, v72
	v_cndmask_b32_e64 v73, 0, v184, s[74:75]
	v_mul_f32_e32 v75, v67, v226
	v_ldexp_f32 v72, v72, v73
	v_mul_f32_e32 v73, v66, v225
	v_cndmask_b32_e64 v73, v73, v74, s[66:67]
	v_cmp_gt_f32_e64 s[74:75], s3, v73
	s_nop 1
	v_cndmask_b32_e64 v74, 0, v183, s[74:75]
	v_add_f32_e32 v73, v73, v74
	v_exp_f32_e32 v73, v73
	v_cndmask_b32_e64 v74, 0, v184, s[74:75]
	v_ldexp_f32 v74, v73, v74
	v_mul_f32_e32 v73, v66, v227
	v_cndmask_b32_e64 v73, v73, v75, s[68:69]
	v_cmp_gt_f32_e64 s[74:75], s3, v73
	s_nop 1
	v_cndmask_b32_e64 v75, 0, v183, s[74:75]
	v_add_f32_e32 v73, v73, v75
	v_exp_f32_e32 v73, v73
	v_cndmask_b32_e64 v75, 0, v184, s[74:75]
	v_ldexp_f32 v73, v73, v75
	v_pk_mul_f32 v[64:65], v[64:65], v[72:73]
	v_mul_f32_e32 v72, v66, v229
	v_mul_f32_e32 v73, v67, v228
	v_cndmask_b32_e64 v72, v72, v73, s[70:71]
	v_cmp_gt_f32_e64 s[74:75], s3, v72
	v_cvt_pk_bf16_f32 v63, v64, v65
	v_cvt_pk_bf16_f32 v64, v68, v69
	v_cndmask_b32_e64 v73, 0, v183, s[74:75]
	v_mul_f32_e32 v68, v66, v103
	v_add_f32_e32 v72, v72, v73
	v_cndmask_b32_e64 v73, 0, v184, s[74:75]
	v_cmp_gt_f32_e64 s[74:75], s3, v68
	v_exp_f32_e32 v72, v72
	v_and_b32_e32 v69, 0xffff0000, v46
	v_cndmask_b32_e64 v68, 0, v183, s[74:75]
	v_fmac_f32_e32 v68, v66, v103
	v_exp_f32_e32 v66, v68
	v_ldexp_f32 v75, v72, v73
	v_cndmask_b32_e64 v68, 0, v184, s[74:75]
	v_pk_mul_f32 v[70:71], v[70:71], v[74:75]
	v_ldexp_f32 v74, v66, v68
	v_mul_f32_e32 v66, v67, v105
	v_cmp_gt_f32_e64 s[74:75], s3, v66
	v_lshlrev_b32_e32 v68, 16, v46
	v_cvt_pk_bf16_f32 v65, v70, v71
	v_cndmask_b32_e64 v66, 0, v183, s[74:75]
	v_fmac_f32_e32 v66, v67, v105
	v_exp_f32_e32 v66, v66
	v_cndmask_b32_e64 v67, 0, v184, s[74:75]
	v_ldexp_f32 v76, v66, v67
	v_pk_mul_f32 v[66:67], v[74:75], v[68:69] op_sel_hi:[0,1]
	v_pk_mul_f32 v[68:69], v[76:77], v[68:69] op_sel_hi:[0,1]
	v_cvt_pk_bf16_f32 v46, v68, v69
	v_lshlrev_b32_e32 v68, 16, v47
	v_and_b32_e32 v69, 0xffff0000, v47
	v_pk_mul_f32 v[70:71], v[74:75], v[68:69] op_sel_hi:[0,1]
	v_cvt_pk_bf16_f32 v66, v66, v67
	v_cvt_pk_bf16_f32 v67, v70, v71
	v_pk_mul_f32 v[68:69], v[76:77], v[68:69] op_sel_hi:[0,1]
	v_lshlrev_b32_e32 v70, 16, v48
	v_and_b32_e32 v71, 0xffff0000, v48
	v_cvt_pk_bf16_f32 v47, v68, v69
	v_pk_mul_f32 v[68:69], v[74:75], v[70:71] op_sel_hi:[0,1]
	v_pk_mul_f32 v[70:71], v[76:77], v[70:71] op_sel_hi:[0,1]
	v_cvt_pk_bf16_f32 v48, v70, v71
	v_lshlrev_b32_e32 v70, 16, v49
	v_and_b32_e32 v71, 0xffff0000, v49
	v_pk_mul_f32 v[72:73], v[74:75], v[70:71] op_sel_hi:[0,1]
	v_cvt_pk_bf16_f32 v68, v68, v69
	v_cvt_pk_bf16_f32 v69, v72, v73
	v_pk_mul_f32 v[70:71], v[76:77], v[70:71] op_sel_hi:[0,1]
	v_lshlrev_b32_e32 v72, 16, v42
	v_and_b32_e32 v73, 0xffff0000, v42
	v_cvt_pk_bf16_f32 v49, v70, v71
	v_pk_mul_f32 v[70:71], v[74:75], v[72:73] op_sel_hi:[0,1]
	v_pk_mul_f32 v[72:73], v[76:77], v[72:73] op_sel_hi:[0,1]
	v_cvt_pk_bf16_f32 v42, v72, v73
	v_lshlrev_b32_e32 v72, 16, v43
	v_and_b32_e32 v73, 0xffff0000, v43
	v_pk_mul_f32 v[78:79], v[74:75], v[72:73] op_sel_hi:[0,1]
	v_cvt_pk_bf16_f32 v70, v70, v71
	v_cvt_pk_bf16_f32 v71, v78, v79
	v_pk_mul_f32 v[72:73], v[76:77], v[72:73] op_sel_hi:[0,1]
	v_lshlrev_b32_e32 v78, 16, v44
	v_and_b32_e32 v79, 0xffff0000, v44
	v_cvt_pk_bf16_f32 v43, v72, v73
	v_pk_mul_f32 v[72:73], v[74:75], v[78:79] op_sel_hi:[0,1]
	v_pk_mul_f32 v[78:79], v[76:77], v[78:79] op_sel_hi:[0,1]
	v_cvt_pk_bf16_f32 v44, v78, v79
	v_lshlrev_b32_e32 v78, 16, v45
	v_and_b32_e32 v79, 0xffff0000, v45
	v_pk_mul_f32 v[74:75], v[74:75], v[78:79] op_sel_hi:[0,1]
	v_cvt_pk_bf16_f32 v72, v72, v73
	v_cvt_pk_bf16_f32 v73, v74, v75
	v_pk_mul_f32 v[74:75], v[76:77], v[78:79] op_sel_hi:[0,1]
	v_cvt_pk_bf16_f32 v45, v74, v75
	ds_read2_b64 v[74:77], v82 offset1:4
	ds_read2_b64 v[78:81], v82 offset0:8 offset1:12
	s_waitcnt lgkmcnt(1)
	v_mfma_f32_16x16x32_bf16 v[74:77], v[50:53], v[74:77], 0
	s_waitcnt lgkmcnt(0)
	v_mfma_f32_16x16x32_bf16 v[74:77], v[54:57], v[78:81], v[74:77]
	ds_read2_b64 v[78:81], v82 offset0:16 offset1:20
	s_waitcnt lgkmcnt(0)
	v_mfma_f32_16x16x32_bf16 v[74:77], v[58:61], v[78:81], v[74:77]
	ds_read2_b64 v[78:81], v82 offset0:24 offset1:28
	s_waitcnt lgkmcnt(0)
	v_mfma_f32_16x16x32_bf16 v[74:77], v[62:65], v[78:81], v[74:77]
	ds_read_b128 v[78:81], v231 offset:53248
	ds_read_b128 v[82:85], v232
	s_waitcnt lgkmcnt(1)
	v_mfma_f32_16x16x32_bf16 v[74:77], v[66:69], v[78:81], v[74:77]
	s_waitcnt lgkmcnt(0)
	v_mfma_f32_16x16x32_bf16 v[74:77], v[46:49], v[82:85], v[74:77]
	ds_read_b128 v[78:81], v231 offset:53312
	ds_read_b128 v[82:85], v232 offset:64
	s_waitcnt lgkmcnt(1)
	v_mfma_f32_16x16x32_bf16 v[74:77], v[70:73], v[78:81], v[74:77]
	s_waitcnt lgkmcnt(0)
	v_mfma_f32_16x16x32_bf16 v[74:77], v[42:45], v[82:85], v[74:77]
	v_add_u32_e32 v78, 0x1100, v230
	v_add_u32_e32 v86, 0x4800, v78
	ds_read2_b64 v[78:81], v86 offset1:4
	ds_read2_b64 v[82:85], v86 offset0:8 offset1:12
	s_waitcnt lgkmcnt(1)
; #define LAS __attribute__((address_space(3)))
; __device__ __forceinline__ void ret_out_phase(const Args& A, Frame& F, int l, bool lastl, bf16_t* ARET, bf16_t* ALRU) {
;     ...
;         f32x4 O[8];
; #pragma unroll
;         for (int dvt = 0; dvt < 8; ++dvt) {
;             f32x4 o = (f32x4){0.f, 0.f, 0.f, 0.f};
; #pragma unroll
;             for (int jp = 0; jp < 4; ++jp) {
;                 const u32x2 lo = *(const LAS u32x2*)(vts + (16 * dvt + fr) * 136 + 32 * jp + 4 * fq);
;                 const u32x2 hi = *(const LAS u32x2*)(vts + (16 * dvt + fr) * 136 + 32 * jp + 16 + 4 * fq);
;                 u32x4 bv; bv[0] = lo.x; bv[1] = lo.y; bv[2] = hi.x; bv[3] = hi.y;
;                 o = __builtin_amdgcn_mfma_f32_16x16x32_bf16(pa[jp], __builtin_bit_cast(bf16x8, bv), o, 0, 0, 0);
;             }
; #pragma unroll
;             for (int ks = 0; ks < 2; ++ks) {
;                 const bf16x8 sf = *(const LAS bf16x8*)(sfs + (16 * dvt + fr) * 72 + 32 * ks + 8 * fq);
;                 const bf16x8 sb = *(const LAS bf16x8*)(sbs + (16 * dvt + fr) * 72 + 32 * ks + 8 * fq);
;                 o = __builtin_amdgcn_mfma_f32_16x16x32_bf16(qF[ks], sf, o, 0, 0, 0);
;                 o = __builtin_amdgcn_mfma_f32_16x16x32_bf16(qB[ks], sb, o, 0, 0, 0);
;             }
;             O[dvt] = o;
;             __builtin_amdgcn_sched_barrier(0);
;         }
	v_mfma_f32_16x16x32_bf16 v[78:81], v[50:53], v[78:81], 0
	s_waitcnt lgkmcnt(0)
	v_mfma_f32_16x16x32_bf16 v[78:81], v[54:57], v[82:85], v[78:81]
	ds_read2_b64 v[82:85], v86 offset0:16 offset1:20
	s_waitcnt lgkmcnt(0)
	v_mfma_f32_16x16x32_bf16 v[78:81], v[58:61], v[82:85], v[78:81]
	ds_read2_b64 v[82:85], v86 offset0:24 offset1:28
	s_waitcnt lgkmcnt(0)
	v_mfma_f32_16x16x32_bf16 v[78:81], v[62:65], v[82:85], v[78:81]
	ds_read_b128 v[82:85], v231 offset:55552
	s_waitcnt lgkmcnt(0)
	v_mfma_f32_16x16x32_bf16 v[78:81], v[66:69], v[82:85], v[78:81]
	ds_read_b128 v[82:85], v233
	s_waitcnt lgkmcnt(0)
	v_mfma_f32_16x16x32_bf16 v[78:81], v[46:49], v[82:85], v[78:81]
	ds_read_b128 v[82:85], v231 offset:55616
	s_waitcnt lgkmcnt(0)
	v_mfma_f32_16x16x32_bf16 v[78:81], v[70:73], v[82:85], v[78:81]
	ds_read_b128 v[82:85], v233 offset:64
	s_waitcnt lgkmcnt(0)
	v_mfma_f32_16x16x32_bf16 v[78:81], v[42:45], v[82:85], v[78:81]
	v_add_u32_e32 v82, 0x2200, v230
	v_add_u32_e32 v90, 0x4800, v82
	ds_read2_b64 v[82:85], v90 offset1:4
	ds_read2_b64 v[86:89], v90 offset0:8 offset1:12
	s_waitcnt lgkmcnt(1)
	v_mfma_f32_16x16x32_bf16 v[82:85], v[50:53], v[82:85], 0
	s_waitcnt lgkmcnt(0)
	v_mfma_f32_16x16x32_bf16 v[82:85], v[54:57], v[86:89], v[82:85]
	ds_read2_b64 v[86:89], v90 offset0:16 offset1:20
	s_waitcnt lgkmcnt(0)
	v_mfma_f32_16x16x32_bf16 v[82:85], v[58:61], v[86:89], v[82:85]
	ds_read2_b64 v[86:89], v90 offset0:24 offset1:28
	s_waitcnt lgkmcnt(0)
	v_mfma_f32_16x16x32_bf16 v[82:85], v[62:65], v[86:89], v[82:85]
	ds_read_b128 v[86:89], v231 offset:57856
	s_waitcnt lgkmcnt(0)
	v_mfma_f32_16x16x32_bf16 v[82:85], v[66:69], v[86:89], v[82:85]
	ds_read_b128 v[86:89], v234
	s_waitcnt lgkmcnt(0)
	v_mfma_f32_16x16x32_bf16 v[82:85], v[46:49], v[86:89], v[82:85]
	ds_read_b128 v[86:89], v231 offset:57920
	s_waitcnt lgkmcnt(0)
	v_mfma_f32_16x16x32_bf16 v[82:85], v[70:73], v[86:89], v[82:85]
	ds_read_b128 v[86:89], v234 offset:64
	s_waitcnt lgkmcnt(0)
	v_mfma_f32_16x16x32_bf16 v[82:85], v[42:45], v[86:89], v[82:85]
	v_add_u32_e32 v86, 0x3300, v230
	v_add_u32_e32 v94, 0x4800, v86
	ds_read2_b64 v[86:89], v94 offset1:4
	ds_read2_b64 v[90:93], v94 offset0:8 offset1:12
	s_waitcnt lgkmcnt(1)
	v_mfma_f32_16x16x32_bf16 v[86:89], v[50:53], v[86:89], 0
	s_waitcnt lgkmcnt(0)
	v_mfma_f32_16x16x32_bf16 v[86:89], v[54:57], v[90:93], v[86:89]
	ds_read2_b64 v[90:93], v94 offset0:16 offset1:20
	s_waitcnt lgkmcnt(0)
	v_mfma_f32_16x16x32_bf16 v[86:89], v[58:61], v[90:93], v[86:89]
	ds_read2_b64 v[90:93], v94 offset0:24 offset1:28
	s_waitcnt lgkmcnt(0)
	v_mfma_f32_16x16x32_bf16 v[86:89], v[62:65], v[90:93], v[86:89]
	ds_read_b128 v[90:93], v160 offset:55552
	s_waitcnt lgkmcnt(0)
	v_mfma_f32_16x16x32_bf16 v[86:89], v[66:69], v[90:93], v[86:89]
	ds_read_b128 v[90:93], v235
	s_waitcnt lgkmcnt(0)
	v_mfma_f32_16x16x32_bf16 v[86:89], v[46:49], v[90:93], v[86:89]
	ds_read_b128 v[90:93], v160 offset:55616
	s_waitcnt lgkmcnt(0)
	v_mfma_f32_16x16x32_bf16 v[86:89], v[70:73], v[90:93], v[86:89]
	ds_read_b128 v[90:93], v235 offset:64
	s_waitcnt lgkmcnt(0)
	v_mfma_f32_16x16x32_bf16 v[86:89], v[42:45], v[90:93], v[86:89]
	v_add_u32_e32 v90, 0x4400, v230
	v_add_u32_e32 v98, 0x4800, v90
	ds_read2_b64 v[90:93], v98 offset1:4
	ds_read2_b64 v[94:97], v98 offset0:8 offset1:12
	s_waitcnt lgkmcnt(1)
	v_mfma_f32_16x16x32_bf16 v[90:93], v[50:53], v[90:93], 0
	s_waitcnt lgkmcnt(0)
	v_mfma_f32_16x16x32_bf16 v[90:93], v[54:57], v[94:97], v[90:93]
	ds_read2_b64 v[94:97], v98 offset0:16 offset1:20
	s_waitcnt lgkmcnt(0)
	v_mfma_f32_16x16x32_bf16 v[90:93], v[58:61], v[94:97], v[90:93]
	ds_read2_b64 v[94:97], v98 offset0:24 offset1:28
	s_waitcnt lgkmcnt(0)
	v_mfma_f32_16x16x32_bf16 v[90:93], v[62:65], v[94:97], v[90:93]
	ds_read_b128 v[94:97], v236 offset:53248
	s_waitcnt lgkmcnt(0)
	v_mfma_f32_16x16x32_bf16 v[90:93], v[66:69], v[94:97], v[90:93]
	ds_read_b128 v[94:97], v237
	s_waitcnt lgkmcnt(0)
	v_mfma_f32_16x16x32_bf16 v[90:93], v[46:49], v[94:97], v[90:93]
	ds_read_b128 v[94:97], v236 offset:53312
	s_waitcnt lgkmcnt(0)
	v_mfma_f32_16x16x32_bf16 v[90:93], v[70:73], v[94:97], v[90:93]
	ds_read_b128 v[94:97], v237 offset:64
	s_waitcnt lgkmcnt(0)
	v_mfma_f32_16x16x32_bf16 v[90:93], v[42:45], v[94:97], v[90:93]
	v_add_u32_e32 v94, 0x5500, v230
	v_add_u32_e32 v129, 0x4800, v94
	ds_read2_b64 v[94:97], v129 offset1:4
	ds_read2_b64 v[98:101], v129 offset0:8 offset1:12
	s_waitcnt lgkmcnt(1)
	v_mfma_f32_16x16x32_bf16 v[94:97], v[50:53], v[94:97], 0
	s_waitcnt lgkmcnt(0)
	v_mfma_f32_16x16x32_bf16 v[94:97], v[54:57], v[98:101], v[94:97]
	ds_read2_b64 v[98:101], v129 offset0:16 offset1:20
	s_waitcnt lgkmcnt(0)
	v_mfma_f32_16x16x32_bf16 v[94:97], v[58:61], v[98:101], v[94:97]
	ds_read2_b64 v[98:101], v129 offset0:24 offset1:28
	s_waitcnt lgkmcnt(0)
	v_mfma_f32_16x16x32_bf16 v[94:97], v[62:65], v[98:101], v[94:97]
	ds_read_b128 v[98:101], v238 offset:53248
	s_waitcnt lgkmcnt(0)
	v_mfma_f32_16x16x32_bf16 v[94:97], v[66:69], v[98:101], v[94:97]
	ds_read_b128 v[98:101], v239
	s_waitcnt lgkmcnt(0)
	v_mfma_f32_16x16x32_bf16 v[94:97], v[46:49], v[98:101], v[94:97]
	ds_read_b128 v[98:101], v238 offset:53312
	s_waitcnt lgkmcnt(0)
	v_mfma_f32_16x16x32_bf16 v[94:97], v[70:73], v[98:101], v[94:97]
	ds_read_b128 v[98:101], v239 offset:64
	s_waitcnt lgkmcnt(0)
	v_mfma_f32_16x16x32_bf16 v[94:97], v[42:45], v[98:101], v[94:97]
	v_add_u32_e32 v98, 0x6600, v230
	v_add_u32_e32 v129, 0x4800, v98
	ds_read2_b64 v[98:101], v129 offset1:4
	ds_read2_b64 v[250:253], v129 offset0:8 offset1:12
	s_waitcnt lgkmcnt(1)
	v_mfma_f32_16x16x32_bf16 v[98:101], v[50:53], v[98:101], 0
	s_waitcnt lgkmcnt(0)
; #define LAS __attribute__((address_space(3)))
; __device__ __forceinline__ void ret_out_phase(const Args& A, Frame& F, int l, bool lastl, bf16_t* ARET, bf16_t* ALRU) {
;     ...
;         for (int dvt = 0; dvt < 8; ++dvt) {
;             f32x4 o = (f32x4){0.f, 0.f, 0.f, 0.f};
; #pragma unroll
;             for (int jp = 0; jp < 4; ++jp) {
;                 const u32x2 lo = *(const LAS u32x2*)(vts + (16 * dvt + fr) * 136 + 32 * jp + 4 * fq);
;                 const u32x2 hi = *(const LAS u32x2*)(vts + (16 * dvt + fr) * 136 + 32 * jp + 16 + 4 * fq);
;                 u32x4 bv; bv[0] = lo.x; bv[1] = lo.y; bv[2] = hi.x; bv[3] = hi.y;
;                 o = __builtin_amdgcn_mfma_f32_16x16x32_bf16(pa[jp], __builtin_bit_cast(bf16x8, bv), o, 0, 0, 0);
;             }
; #pragma unroll
;             for (int ks = 0; ks < 2; ++ks) {
;                 const bf16x8 sf = *(const LAS bf16x8*)(sfs + (16 * dvt + fr) * 72 + 32 * ks + 8 * fq);
;                 const bf16x8 sb = *(const LAS bf16x8*)(sbs + (16 * dvt + fr) * 72 + 32 * ks + 8 * fq);
;                 o = __builtin_amdgcn_mfma_f32_16x16x32_bf16(qF[ks], sf, o, 0, 0, 0);
;                 o = __builtin_amdgcn_mfma_f32_16x16x32_bf16(qB[ks], sb, o, 0, 0, 0);
;             }
;             O[dvt] = o;
;             __builtin_amdgcn_sched_barrier(0);
;         }
; #pragma unroll
;         for (int r = 0; r < 4; ++r) {
;             float sm = 0.f;
; #pragma unroll
;             for (int dvt = 0; dvt < 8; ++dvt) sm += O[dvt][r];
;             const float mu = sum16(sm) * (1.f / DV);
;             float q2 = 0.f;
; #pragma unroll
;             for (int dvt = 0; dvt < 8; ++dvt) { const float dd = O[dvt][r] - mu; q2 += dd * dd; }
;             const float rstd = rsqrtf(sum16(q2) * (1.f / DV) + EPS);
	v_mfma_f32_16x16x32_bf16 v[98:101], v[54:57], v[250:253], v[98:101]
	ds_read2_b64 v[250:253], v129 offset0:16 offset1:20
	s_waitcnt lgkmcnt(0)
	v_mfma_f32_16x16x32_bf16 v[98:101], v[58:61], v[250:253], v[98:101]
	ds_read2_b64 v[250:253], v129 offset0:24 offset1:28
	s_waitcnt lgkmcnt(0)
	v_mfma_f32_16x16x32_bf16 v[98:101], v[62:65], v[250:253], v[98:101]
	ds_read_b128 v[250:253], v240 offset:53248
	s_waitcnt lgkmcnt(0)
	v_mfma_f32_16x16x32_bf16 v[98:101], v[66:69], v[250:253], v[98:101]
	ds_read_b128 v[250:253], v241
	s_waitcnt lgkmcnt(0)
	v_mfma_f32_16x16x32_bf16 v[98:101], v[46:49], v[250:253], v[98:101]
	ds_read_b128 v[250:253], v240 offset:53312
	s_waitcnt lgkmcnt(0)
	v_mfma_f32_16x16x32_bf16 v[98:101], v[70:73], v[250:253], v[98:101]
	ds_read_b128 v[250:253], v241 offset:64
	s_waitcnt lgkmcnt(0)
	v_mfma_f32_16x16x32_bf16 v[98:101], v[42:45], v[250:253], v[98:101]
	v_add_u32_e32 v129, 0x4800, v242
	ds_read2_b64 v[250:253], v129 offset1:4
	s_waitcnt lgkmcnt(0)
	v_mfma_f32_16x16x32_bf16 v[50:53], v[50:53], v[250:253], 0
	ds_read2_b64 v[250:253], v129 offset0:8 offset1:12
	s_waitcnt lgkmcnt(0)
	v_mfma_f32_16x16x32_bf16 v[50:53], v[54:57], v[250:253], v[50:53]
	ds_read2_b64 v[54:57], v129 offset0:16 offset1:20
	s_waitcnt lgkmcnt(0)
	v_mfma_f32_16x16x32_bf16 v[50:53], v[58:61], v[54:57], v[50:53]
	ds_read2_b64 v[54:57], v129 offset0:24 offset1:28
	s_waitcnt lgkmcnt(0)
	v_mfma_f32_16x16x32_bf16 v[50:53], v[62:65], v[54:57], v[50:53]
	ds_read_b128 v[54:57], v243 offset:53248
	ds_read_b128 v[58:61], v243 offset:53312
	s_waitcnt lgkmcnt(1)
	v_mfma_f32_16x16x32_bf16 v[50:53], v[66:69], v[54:57], v[50:53]
	ds_read_b128 v[54:57], v244
	ds_read_b128 v[62:65], v244 offset:64
	s_waitcnt lgkmcnt(1)
	v_mfma_f32_16x16x32_bf16 v[46:49], v[46:49], v[54:57], v[50:53]
	v_mfma_f32_16x16x32_bf16 v[46:49], v[70:73], v[58:61], v[46:49]
	s_waitcnt lgkmcnt(0)
	v_mfma_f32_16x16x32_bf16 v[42:45], v[42:45], v[62:65], v[46:49]
	s_nop 5
	v_add_f32_e64 v46, v74, 0
	v_add_f32_e64 v47, v75, 0
	v_mov_b32_e32 v50, v86
	v_pk_add_f32 v[46:47], v[46:47], v[78:79]
	v_mov_b32_e32 v51, v82
	v_pk_add_f32 v[46:47], v[46:47], v[82:83]
	v_mov_b32_e32 v82, v87
	v_pk_add_f32 v[46:47], v[46:47], v[86:87]
	v_mov_b32_e32 v52, v94
	v_pk_add_f32 v[46:47], v[46:47], v[90:91]
	v_mov_b32_e32 v53, v90
	v_pk_add_f32 v[46:47], v[46:47], v[94:95]
	v_mov_b32_e32 v90, v95
	v_pk_add_f32 v[46:47], v[46:47], v[98:99]
	v_mov_b32_e32 v54, v42
	v_pk_add_f32 v[46:47], v[46:47], v[42:43]
	ds_bpermute_b32 v48, v127, v46
	ds_bpermute_b32 v49, v127, v47
	v_mov_b32_e32 v55, v98
	v_mov_b32_e32 v98, v43
	s_mov_b32 s2, 0x358637bd
	s_add_i32 vcc_hi, vcc_hi, s34
	s_waitcnt lgkmcnt(0)
	v_pk_add_f32 v[46:47], v[46:47], v[48:49]
	ds_bpermute_b32 v48, v130, v46
	ds_bpermute_b32 v49, v130, v47
	s_add_i32 s61, s61, s60
	s_cmp_lg_u32 s37, s39
	s_waitcnt lgkmcnt(0)
	v_pk_add_f32 v[46:47], v[46:47], v[48:49]
	ds_bpermute_b32 v48, v131, v46
	ds_bpermute_b32 v49, v131, v47
	s_waitcnt lgkmcnt(0)
	v_pk_add_f32 v[46:47], v[46:47], v[48:49]
	ds_bpermute_b32 v48, v132, v46
	ds_bpermute_b32 v49, v132, v47
	s_waitcnt lgkmcnt(0)
	v_pk_add_f32 v[46:47], v[46:47], v[48:49]
	s_nop 0
	v_pk_mul_f32 v[48:49], v[46:47], s[18:19] op_sel_hi:[1,0]
	v_pk_fma_f32 v[64:65], v[46:47], s[18:19], v[78:79] op_sel_hi:[1,0,1] neg_lo:[1,0,0] neg_hi:[1,0,0]
	v_pk_add_f32 v[50:51], v[50:51], v[48:49] op_sel_hi:[1,0] neg_lo:[0,1] neg_hi:[0,1]
	v_pk_add_f32 v[68:69], v[82:83], v[48:49] op_sel:[0,1] neg_lo:[0,1] neg_hi:[0,1]
	v_pk_fma_f32 v[56:57], v[46:47], s[18:19], v[74:75] op_sel_hi:[1,0,1] neg_lo:[1,0,0] neg_hi:[1,0,0]
	v_pk_mul_f32 v[58:59], v[50:51], v[50:51]
	v_pk_mul_f32 v[46:47], v[64:65], v[64:65]
	v_pk_mul_f32 v[70:71], v[68:69], v[68:69]
	v_pk_add_f32 v[52:53], v[52:53], v[48:49] op_sel_hi:[1,0] neg_lo:[0,1] neg_hi:[0,1]
	v_pk_fma_f32 v[66:67], v[56:57], v[56:57], v[46:47]
	v_pk_add_f32 v[46:47], v[90:91], v[48:49] op_sel:[0,1] neg_lo:[0,1] neg_hi:[0,1]
	v_mov_b32_e32 v75, v58
	v_mov_b32_e32 v58, v71
	v_pk_mul_f32 v[60:61], v[52:53], v[52:53]
	v_pk_mul_f32 v[72:73], v[46:47], v[46:47]
	v_mov_b32_e32 v74, v70
	v_pk_add_f32 v[58:59], v[58:59], v[66:67] op_sel:[0,1] op_sel_hi:[1,0]
	v_pk_add_f32 v[54:55], v[54:55], v[48:49] op_sel_hi:[1,0] neg_lo:[0,1] neg_hi:[0,1]
	v_pk_add_f32 v[42:43], v[98:99], v[48:49] op_sel:[0,1] neg_lo:[0,1] neg_hi:[0,1]
	v_pk_add_f32 v[58:59], v[74:75], v[58:59]
	v_mov_b32_e32 v66, v73
	v_mov_b32_e32 v67, v61
	v_pk_mul_f32 v[62:63], v[54:55], v[54:55]
	v_pk_mul_f32 v[48:49], v[42:43], v[42:43]
	v_pk_add_f32 v[58:59], v[66:67], v[58:59]
	v_mov_b32_e32 v73, v60
	v_pk_add_f32 v[58:59], v[72:73], v[58:59]
	v_mov_b32_e32 v60, v49
	v_mov_b32_e32 v61, v63
	v_pk_add_f32 v[58:59], v[60:61], v[58:59]
	v_mov_b32_e32 v49, v62
	v_pk_add_f32 v[48:49], v[48:49], v[58:59]
	ds_bpermute_b32 v59, v127, v49
	ds_bpermute_b32 v58, v127, v48
	s_waitcnt lgkmcnt(0)
	v_pk_add_f32 v[48:49], v[48:49], v[58:59]
	ds_bpermute_b32 v59, v130, v49
	ds_bpermute_b32 v58, v130, v48
	s_waitcnt lgkmcnt(0)
	v_pk_add_f32 v[48:49], v[48:49], v[58:59]
	ds_bpermute_b32 v59, v131, v49
	ds_bpermute_b32 v58, v131, v48
	s_waitcnt lgkmcnt(0)
	v_pk_add_f32 v[48:49], v[48:49], v[58:59]
	ds_bpermute_b32 v59, v132, v49
	ds_bpermute_b32 v58, v132, v48
	s_waitcnt lgkmcnt(0)
; __device__ __forceinline__ bf16_t f2bf(float f) { return (bf16_t)(pk2(f, 0.f) & 0xffffu); }
; __device__ __forceinline__ void ret_out_phase(const Args& A, Frame& F, int l, bool lastl, bf16_t* ARET, bf16_t* ALRU) {
;     ...
; #pragma unroll
;         for (int r = 0; r < 4; ++r) {
;             float sm = 0.f;
; #pragma unroll
;             for (int dvt = 0; dvt < 8; ++dvt) sm += O[dvt][r];
;             const float mu = sum16(sm) * (1.f / DV);
;             float q2 = 0.f;
; #pragma unroll
;             for (int dvt = 0; dvt < 8; ++dvt) { const float dd = O[dvt][r] - mu; q2 += dd * dd; }
;             const float rstd = rsqrtf(sum16(q2) * (1.f / DV) + EPS);
; #pragma unroll
;             for (int dvt = 0; dvt < 8; ++dvt) os[(16 * w + 4 * fq + r) * 136 + 16 * dvt + fr] = f2bf((O[dvt][r] - mu) * rstd);
;         }
	v_pk_add_f32 v[48:49], v[48:49], v[58:59]
	v_mov_b64_e32 v[58:59], s[2:3]
	v_pk_fma_f32 v[48:49], v[48:49], s[18:19], v[58:59] op_sel_hi:[1,0,0]
	s_mov_b32 s2, 0xfcc8000
	v_mul_f32_e32 v60, 0x4b800000, v49
	v_cmp_gt_f32_e64 s[74:75], s33, v49
	s_nop 1
	v_cndmask_b32_e64 v49, v49, v60, s[74:75]
	v_rsq_f32_e32 v49, v49
	s_nop 0
	v_mul_f32_e32 v60, 0x45800000, v49
	v_cndmask_b32_e64 v49, v49, v60, s[74:75]
	v_mul_f32_e32 v50, v50, v49
	v_cvt_pk_bf16_f32 v50, v50, s0
	ds_write_b16 v249, v50 offset:96
	v_mul_f32_e32 v50, v53, v49
	v_cvt_pk_bf16_f32 v50, v50, s0
	v_mul_f32_e32 v56, v56, v49
	ds_write_b16 v249, v50 offset:128
	v_mul_f32_e32 v50, v52, v49
	v_cvt_pk_bf16_f32 v56, v56, s0
	v_cvt_pk_bf16_f32 v50, v50, s0
	ds_write_b16 v249, v56
	v_mul_f32_e32 v56, v64, v49
	v_mul_f32_e32 v51, v51, v49
	ds_write_b16 v249, v50 offset:160
	v_mul_f32_e32 v50, v55, v49
	v_mul_f32_e32 v52, v54, v49
	v_mul_f32_e32 v49, 0x4b800000, v48
	v_cmp_gt_f32_e64 s[74:75], s33, v48
	v_cvt_pk_bf16_f32 v51, v51, s0
	v_cvt_pk_bf16_f32 v50, v50, s0
	v_cndmask_b32_e64 v48, v48, v49, s[74:75]
	v_rsq_f32_e32 v53, v48
	v_pk_add_f32 v[48:49], v[76:77], 0 op_sel_hi:[1,0]
	ds_write_b16 v249, v51 offset:64
	v_pk_add_f32 v[48:49], v[48:49], v[80:81]
	ds_write_b16 v249, v50 offset:192
	v_pk_add_f32 v[48:49], v[48:49], v[84:85]
	v_cvt_pk_bf16_f32 v52, v52, s0
	v_pk_add_f32 v[48:49], v[48:49], v[88:89]
	ds_write_b16 v249, v52 offset:224
	v_pk_add_f32 v[48:49], v[48:49], v[92:93]
	v_mul_f32_e32 v52, 0x45800000, v53
	v_pk_add_f32 v[48:49], v[48:49], v[96:97]
	v_cndmask_b32_e64 v82, v53, v52, s[74:75]
	v_pk_add_f32 v[48:49], v[48:49], v[100:101]
	v_mul_f32_e32 v52, v57, v82
	v_pk_add_f32 v[48:49], v[48:49], v[44:45]
	ds_bpermute_b32 v50, v127, v48
	ds_bpermute_b32 v51, v127, v49
	v_cvt_pk_bf16_f32 v52, v52, s0
	ds_write_b16 v249, v52 offset:272
	v_mul_f32_e32 v52, v65, v82
	v_cvt_pk_bf16_f32 v83, v52, s0
	s_waitcnt lgkmcnt(1)
	v_pk_add_f32 v[48:49], v[48:49], v[50:51]
	ds_bpermute_b32 v50, v130, v48
	ds_bpermute_b32 v51, v130, v49
	v_mov_b32_e32 v52, v88
	v_mov_b32_e32 v53, v84
	v_mov_b32_e32 v84, v89
	v_mov_b32_e32 v54, v96
	s_waitcnt lgkmcnt(0)
	v_pk_add_f32 v[48:49], v[48:49], v[50:51]
	ds_bpermute_b32 v50, v131, v48
	ds_bpermute_b32 v51, v131, v49
	v_mov_b32_e32 v55, v92
	v_mov_b32_e32 v92, v97
	v_cvt_pk_bf16_f32 v56, v56, s0
	ds_write_b16 v249, v56 offset:32
	s_waitcnt lgkmcnt(1)
	v_pk_add_f32 v[48:49], v[48:49], v[50:51]
	ds_bpermute_b32 v50, v132, v48
	ds_bpermute_b32 v51, v132, v49
	v_mov_b32_e32 v56, v44
	v_mov_b32_e32 v57, v100
	v_mov_b32_e32 v100, v45
	v_mul_f32_e32 v47, v47, v82
	s_waitcnt lgkmcnt(0)
	v_pk_add_f32 v[48:49], v[48:49], v[50:51]
	v_cvt_pk_bf16_f32 v47, v47, s0
	v_pk_mul_f32 v[50:51], v[48:49], s[18:19] op_sel_hi:[1,0]
	v_pk_fma_f32 v[66:67], v[48:49], s[18:19], v[76:77] op_sel_hi:[1,0,1] neg_lo:[1,0,0] neg_hi:[1,0,0]
	v_pk_add_f32 v[52:53], v[52:53], v[50:51] op_sel_hi:[1,0] neg_lo:[0,1] neg_hi:[0,1]
	v_pk_fma_f32 v[48:49], v[48:49], s[18:19], v[80:81] op_sel_hi:[1,0,1] neg_lo:[1,0,0] neg_hi:[1,0,0]
	v_pk_add_f32 v[72:73], v[84:85], v[50:51] op_sel:[0,1] neg_lo:[0,1] neg_hi:[0,1]
	v_pk_mul_f32 v[60:61], v[52:53], v[52:53]
	v_pk_mul_f32 v[70:71], v[48:49], v[48:49]
	v_pk_mul_f32 v[74:75], v[72:73], v[72:73]
	v_pk_add_f32 v[54:55], v[54:55], v[50:51] op_sel_hi:[1,0] neg_lo:[0,1] neg_hi:[0,1]
	v_pk_fma_f32 v[70:71], v[66:67], v[66:67], v[70:71]
	v_pk_add_f32 v[76:77], v[92:93], v[50:51] op_sel:[0,1] neg_lo:[0,1] neg_hi:[0,1]
	v_mov_b32_e32 v81, v60
	v_mov_b32_e32 v60, v75
	v_pk_mul_f32 v[62:63], v[54:55], v[54:55]
	v_pk_mul_f32 v[78:79], v[76:77], v[76:77]
	v_mov_b32_e32 v80, v74
	v_pk_add_f32 v[60:61], v[60:61], v[70:71] op_sel:[0,1] op_sel_hi:[1,0]
	v_pk_add_f32 v[56:57], v[56:57], v[50:51] op_sel_hi:[1,0] neg_lo:[0,1] neg_hi:[0,1]
	v_pk_add_f32 v[44:45], v[100:101], v[50:51] op_sel:[0,1] neg_lo:[0,1] neg_hi:[0,1]
	v_pk_add_f32 v[60:61], v[80:81], v[60:61]
	v_mov_b32_e32 v70, v79
	v_mov_b32_e32 v71, v63
	v_pk_mul_f32 v[64:65], v[56:57], v[56:57]
	v_pk_mul_f32 v[50:51], v[44:45], v[44:45]
	v_pk_add_f32 v[60:61], v[70:71], v[60:61]
	v_mov_b32_e32 v79, v62
	v_pk_add_f32 v[60:61], v[78:79], v[60:61]
	v_mov_b32_e32 v62, v51
	v_mov_b32_e32 v63, v65
	v_pk_add_f32 v[60:61], v[62:63], v[60:61]
	v_mov_b32_e32 v51, v64
	v_pk_add_f32 v[50:51], v[50:51], v[60:61]
	ds_bpermute_b32 v61, v127, v51
	ds_bpermute_b32 v60, v127, v50
	v_mul_f32_e32 v62, v69, v82
	v_cvt_pk_bf16_f32 v62, v62, s0
	ds_write_b16 v249, v62 offset:336
	v_mul_f32_e32 v62, v68, v82
	s_waitcnt lgkmcnt(1)
	v_pk_add_f32 v[50:51], v[50:51], v[60:61]
	ds_bpermute_b32 v61, v130, v51
	ds_bpermute_b32 v60, v130, v50
	v_cvt_pk_bf16_f32 v62, v62, s0
	v_mul_f32_e32 v46, v46, v82
	ds_write_b16 v249, v62 offset:368
	ds_write_b16 v249, v47 offset:400
	s_waitcnt lgkmcnt(2)
	v_pk_add_f32 v[50:51], v[50:51], v[60:61]
	ds_bpermute_b32 v61, v131, v51
	ds_bpermute_b32 v60, v131, v50
	v_cvt_pk_bf16_f32 v62, v46, s0
	v_mul_f32_e32 v43, v43, v82
	v_cvt_pk_bf16_f32 v43, v43, s0
	ds_write_b16 v249, v43 offset:464
	s_waitcnt lgkmcnt(1)
	v_pk_add_f32 v[46:47], v[50:51], v[60:61]
	ds_bpermute_b32 v51, v132, v47
	ds_bpermute_b32 v50, v132, v46
	v_mul_f32_e32 v42, v42, v82
	v_cvt_pk_bf16_f32 v42, v42, s0
	ds_write_b16 v249, v42 offset:496
	ds_write_b16 v249, v83 offset:304
	s_waitcnt lgkmcnt(2)
; #define LAS __attribute__((address_space(3)))
; __device__ __forceinline__ unsigned pk2(float lo, float hi) { const f32x2_t v = {lo, hi}; const bf16v2_t b = __builtin_convertvector(v, bf16v2_t); return __builtin_bit_cast(unsigned, b); }
; __device__ __forceinline__ bf16_t f2bf(float f) { return (bf16_t)(pk2(f, 0.f) & 0xffffu); }
; __device__ __forceinline__ float bflo(unsigned u) { return __uint_as_float(u << 16); }
; __device__ __forceinline__ float bfhi(unsigned u) { return __uint_as_float(u & 0xffff0000u); }
; __device__ __forceinline__ void ret_out_phase(const Args& A, Frame& F, int l, bool lastl, bf16_t* ARET, bf16_t* ALRU) {
;     ...
;             for (int dvt = 0; dvt < 8; ++dvt) os[(16 * w + 4 * fq + r) * 136 + 16 * dvt + fr] = f2bf((O[dvt][r] - mu) * rstd);
;         }
;         __builtin_amdgcn_fence(__ATOMIC_RELEASE, "workgroup"); __builtin_amdgcn_wave_barrier(); __builtin_amdgcn_fence(__ATOMIC_ACQUIRE, "workgroup");
;         {
;             const int rr = 16 * w + (lane >> 2), cc = (lane & 3) * 32;
;             const size_t go = (rowbase + rr) * D + 128 * h + cc;
; #pragma unroll
;             for (int i = 0; i < 4; ++i) {
;                 const u32x4 ov = *(const LAS u32x4*)(os + rr * 136 + cc + 8 * i);
;                 const u32x4 gv = *(const u32x4*)(WSB(WS_SG) + go + 8 * i);
;                 u32x4 rv;
; #pragma unroll
;                 for (int e = 0; e < 4; ++e) rv[e] = pk2(bflo(ov[e]) * bflo(gv[e]), bfhi(ov[e]) * bfhi(gv[e]));
;                 *(u32x4*)(ARET + go + 8 * i) = rv;
;             }
;         }
; #pragma unroll
;         for (int i = 0; i < 4; ++i) {
;             const int u = tid + i * NTHREADS, r = u >> 4, c8 = (u & 15) * 8;
;             const size_t o = (rowbase + r) * D + 128 * h + c8;
;             const u32x4 hf = *(const u32x4*)(WSB(WS_HF) + o), hb = *(const u32x4*)(WSB(WS_HB) + o), gg = *(const u32x4*)(WSB(WS_GG) + o);
;             u32x4 ov;
; #pragma unroll
;             for (int e = 0; e < 4; ++e) ov[e] = pk2((bflo(hf[e]) + bflo(hb[e])) * bflo(gg[e]), (bfhi(hf[e]) + bfhi(hb[e])) * bfhi(gg[e]));
;             *(u32x4*)(ALRU + o) = ov;
;         }
	v_pk_add_f32 v[46:47], v[46:47], v[50:51]
	ds_write_b16 v249, v62 offset:432
	v_pk_fma_f32 v[46:47], v[46:47], s[18:19], v[58:59] op_sel_hi:[1,0,0]
	s_nop 0
	v_mul_f32_e32 v43, 0x4b800000, v47
	v_cmp_gt_f32_e64 s[74:75], s33, v47
	s_nop 1
	v_cndmask_b32_e64 v43, v47, v43, s[74:75]
	v_rsq_f32_e32 v43, v43
	s_nop 0
	v_mul_f32_e32 v42, 0x45800000, v43
	v_cndmask_b32_e64 v42, v43, v42, s[74:75]
	v_mul_f32_e32 v43, v66, v42
	v_cvt_pk_bf16_f32 v43, v43, s0
	ds_write_b16 v249, v43 offset:544
	v_mul_f32_e32 v43, v48, v42
	v_cvt_pk_bf16_f32 v43, v43, s0
	ds_write_b16 v249, v43 offset:576
	v_mul_f32_e32 v43, v53, v42
	v_cvt_pk_bf16_f32 v43, v43, s0
	ds_write_b16 v249, v43 offset:608
	v_mul_f32_e32 v43, v52, v42
	v_cvt_pk_bf16_f32 v43, v43, s0
	ds_write_b16 v249, v43 offset:640
	v_mul_f32_e32 v43, v55, v42
	v_cvt_pk_bf16_f32 v43, v43, s0
	ds_write_b16 v249, v43 offset:672
	v_mul_f32_e32 v43, v54, v42
	v_cvt_pk_bf16_f32 v43, v43, s0
	ds_write_b16 v249, v43 offset:704
	v_mul_f32_e32 v43, v57, v42
	v_cvt_pk_bf16_f32 v43, v43, s0
	ds_write_b16 v249, v43 offset:736
	v_mul_f32_e32 v43, 0x4b800000, v46
	v_cmp_gt_f32_e64 s[74:75], s33, v46
	v_mul_f32_e32 v42, v56, v42
	v_cvt_pk_bf16_f32 v42, v42, s0
	v_cndmask_b32_e64 v43, v46, v43, s[74:75]
	v_rsq_f32_e32 v43, v43
	ds_write_b16 v249, v42 offset:768
	v_mul_f32_e32 v42, 0x45800000, v43
	v_cndmask_b32_e64 v42, v43, v42, s[74:75]
	v_mul_f32_e32 v43, v67, v42
	v_cvt_pk_bf16_f32 v43, v43, s0
	ds_write_b16 v249, v43 offset:816
	v_mul_f32_e32 v43, v49, v42
	v_cvt_pk_bf16_f32 v43, v43, s0
	ds_write_b16 v249, v43 offset:848
	v_mul_f32_e32 v43, v73, v42
	v_cvt_pk_bf16_f32 v43, v43, s0
	ds_write_b16 v249, v43 offset:880
	v_mul_f32_e32 v43, v72, v42
	v_cvt_pk_bf16_f32 v43, v43, s0
	ds_write_b16 v249, v43 offset:912
	v_mul_f32_e32 v43, v77, v42
	v_cvt_pk_bf16_f32 v43, v43, s0
	ds_write_b16 v249, v43 offset:944
	v_mul_f32_e32 v43, v76, v42
	v_cvt_pk_bf16_f32 v43, v43, s0
	ds_write_b16 v249, v43 offset:976
	v_mul_f32_e32 v43, v45, v42
	v_mul_f32_e32 v42, v44, v42
	v_cvt_pk_bf16_f32 v43, v43, s0
	v_cvt_pk_bf16_f32 v42, v42, s0
	ds_write_b16 v249, v43 offset:1008
	ds_write_b16 v249, v42 offset:1040
	v_lshl_add_u64 v[42:43], s[8:9], 0, v[124:125]
	v_lshlrev_b64 v[42:43], 10, v[42:43]
	v_or_b32_e32 v42, v42, v126
	v_or_b32_e32 v42, s82, v42
	v_lshlrev_b64 v[54:55], 1, v[42:43]
	v_lshl_add_u64 v[42:43], s[50:51], 0, v[54:55]
	s_waitcnt lgkmcnt(0)
	v_add_u32_e32 v129, s8, v124
	v_lshlrev_b32_e32 v129, 11, v129
	v_or_b32_e32 v100, s82, v126
	v_lshl_or_b32 v129, v100, 1, v129
	v_or_b32_e32 v100, s82, v104
	v_add_u32_e32 v141, s8, v106
	v_lshlrev_b32_e32 v141, 11, v141
	v_lshl_or_b32 v141, v100, 1, v141
	v_add_u32_e32 v250, s8, v108
	v_lshlrev_b32_e32 v250, 11, v250
	v_lshl_or_b32 v250, v100, 1, v250
	v_add_u32_e32 v251, s8, v110
	v_lshlrev_b32_e32 v251, 11, v251
	v_lshl_or_b32 v251, v100, 1, v251
	v_add_u32_e32 v252, s8, v112
	v_lshlrev_b32_e32 v252, 11, v252
	v_lshl_or_b32 v252, v100, 1, v252
	global_load_dwordx4 v[56:59], v129, s[50:51]
	global_load_dwordx4 v[60:63], v129, s[50:51] offset:16
	global_load_dwordx4 v[64:67], v129, s[50:51] offset:32
	global_load_dwordx4 v[68:71], v129, s[50:51] offset:48
	global_load_dwordx4 v[72:75], v141, s[10:11]
	global_load_dwordx4 v[76:79], v141, s[12:13]
	global_load_dwordx4 v[80:83], v141, s[14:15]
	global_load_dwordx4 v[84:87], v250, s[10:11]
	global_load_dwordx4 v[88:91], v250, s[12:13]
	global_load_dwordx4 v[92:95], v250, s[14:15]
	ds_read_b128 v[96:99], v133
	ds_read_b128 v[44:47], v133 offset:16
	s_waitcnt vmcnt(9) lgkmcnt(1)
	v_lshlrev_b32_e32 v100, 16, v96
	v_and_b32_e32 v101, 0xffff0000, v96
	v_lshlrev_b32_e32 v52, 16, v56
	v_and_b32_e32 v53, 0xffff0000, v56
	v_pk_mul_f32 v[100:101], v[100:101], v[52:53]
	s_nop 0
	v_cvt_pk_bf16_f32 v56, v100, v101
	v_lshlrev_b32_e32 v100, 16, v97
	v_and_b32_e32 v101, 0xffff0000, v97
	v_lshlrev_b32_e32 v52, 16, v57
	v_and_b32_e32 v53, 0xffff0000, v57
	v_pk_mul_f32 v[100:101], v[100:101], v[52:53]
	s_nop 0
	v_cvt_pk_bf16_f32 v57, v100, v101
	v_lshlrev_b32_e32 v100, 16, v98
	v_and_b32_e32 v101, 0xffff0000, v98
	v_lshlrev_b32_e32 v52, 16, v58
	v_and_b32_e32 v53, 0xffff0000, v58
	v_pk_mul_f32 v[100:101], v[100:101], v[52:53]
	s_nop 0
	v_cvt_pk_bf16_f32 v58, v100, v101
	v_lshlrev_b32_e32 v100, 16, v99
	v_and_b32_e32 v101, 0xffff0000, v99
	v_lshlrev_b32_e32 v52, 16, v59
	v_and_b32_e32 v53, 0xffff0000, v59
	v_pk_mul_f32 v[100:101], v[100:101], v[52:53]
	s_nop 0
	v_cvt_pk_bf16_f32 v59, v100, v101
	global_store_dwordx4 v129, v[56:59], s[88:89]
	s_waitcnt vmcnt(9) lgkmcnt(0)
	v_lshlrev_b32_e32 v100, 16, v44
	v_and_b32_e32 v101, 0xffff0000, v44
	v_lshlrev_b32_e32 v52, 16, v60
	v_and_b32_e32 v53, 0xffff0000, v60
	v_pk_mul_f32 v[100:101], v[100:101], v[52:53]
	s_nop 0
	v_cvt_pk_bf16_f32 v60, v100, v101
	v_lshlrev_b32_e32 v100, 16, v45
	v_and_b32_e32 v101, 0xffff0000, v45
	v_lshlrev_b32_e32 v52, 16, v61
	v_and_b32_e32 v53, 0xffff0000, v61
	v_pk_mul_f32 v[100:101], v[100:101], v[52:53]
	s_nop 0
	v_cvt_pk_bf16_f32 v61, v100, v101
	v_lshlrev_b32_e32 v100, 16, v46
	v_and_b32_e32 v101, 0xffff0000, v46
	v_lshlrev_b32_e32 v52, 16, v62
	v_and_b32_e32 v53, 0xffff0000, v62
	v_pk_mul_f32 v[100:101], v[100:101], v[52:53]
	s_nop 0
	v_cvt_pk_bf16_f32 v62, v100, v101
	v_lshlrev_b32_e32 v100, 16, v47
	v_and_b32_e32 v101, 0xffff0000, v47
	v_lshlrev_b32_e32 v52, 16, v63
	v_and_b32_e32 v53, 0xffff0000, v63
	v_pk_mul_f32 v[100:101], v[100:101], v[52:53]
	s_nop 0
	v_cvt_pk_bf16_f32 v63, v100, v101
	global_store_dwordx4 v129, v[60:63], s[88:89] offset:16
	ds_read_b128 v[96:99], v133 offset:32
	ds_read_b128 v[44:47], v133 offset:48
	s_waitcnt vmcnt(9) lgkmcnt(1)
; #define LAS __attribute__((address_space(3)))
; __device__ __forceinline__ unsigned pk2(float lo, float hi) { const f32x2_t v = {lo, hi}; const bf16v2_t b = __builtin_convertvector(v, bf16v2_t); return __builtin_bit_cast(unsigned, b); }
; __device__ __forceinline__ float bflo(unsigned u) { return __uint_as_float(u << 16); }
; __device__ __forceinline__ float bfhi(unsigned u) { return __uint_as_float(u & 0xffff0000u); }
; __device__ __forceinline__ void ret_out_phase(const Args& A, Frame& F, int l, bool lastl, bf16_t* ARET, bf16_t* ALRU) {
;     ...
;             const int rr = 16 * w + (lane >> 2), cc = (lane & 3) * 32;
;             const size_t go = (rowbase + rr) * D + 128 * h + cc;
; #pragma unroll
;             for (int i = 0; i < 4; ++i) {
;                 const u32x4 ov = *(const LAS u32x4*)(os + rr * 136 + cc + 8 * i);
;                 const u32x4 gv = *(const u32x4*)(WSB(WS_SG) + go + 8 * i);
;                 u32x4 rv;
; #pragma unroll
;                 for (int e = 0; e < 4; ++e) rv[e] = pk2(bflo(ov[e]) * bflo(gv[e]), bfhi(ov[e]) * bfhi(gv[e]));
;                 *(u32x4*)(ARET + go + 8 * i) = rv;
;             }
;         }
; #pragma unroll
;         for (int i = 0; i < 4; ++i) {
;             const int u = tid + i * NTHREADS, r = u >> 4, c8 = (u & 15) * 8;
;             const size_t o = (rowbase + r) * D + 128 * h + c8;
;             const u32x4 hf = *(const u32x4*)(WSB(WS_HF) + o), hb = *(const u32x4*)(WSB(WS_HB) + o), gg = *(const u32x4*)(WSB(WS_GG) + o);
;             u32x4 ov;
; #pragma unroll
;             for (int e = 0; e < 4; ++e) ov[e] = pk2((bflo(hf[e]) + bflo(hb[e])) * bflo(gg[e]), (bfhi(hf[e]) + bfhi(hb[e])) * bfhi(gg[e]));
;             *(u32x4*)(ALRU + o) = ov;
;         }
	v_lshlrev_b32_e32 v100, 16, v96
	v_and_b32_e32 v101, 0xffff0000, v96
	v_lshlrev_b32_e32 v52, 16, v64
	v_and_b32_e32 v53, 0xffff0000, v64
	v_pk_mul_f32 v[100:101], v[100:101], v[52:53]
	s_nop 0
	v_cvt_pk_bf16_f32 v64, v100, v101
	v_lshlrev_b32_e32 v100, 16, v97
	v_and_b32_e32 v101, 0xffff0000, v97
	v_lshlrev_b32_e32 v52, 16, v65
	v_and_b32_e32 v53, 0xffff0000, v65
	v_pk_mul_f32 v[100:101], v[100:101], v[52:53]
	s_nop 0
	v_cvt_pk_bf16_f32 v65, v100, v101
	v_lshlrev_b32_e32 v100, 16, v98
	v_and_b32_e32 v101, 0xffff0000, v98
	v_lshlrev_b32_e32 v52, 16, v66
	v_and_b32_e32 v53, 0xffff0000, v66
	v_pk_mul_f32 v[100:101], v[100:101], v[52:53]
	s_nop 0
	v_cvt_pk_bf16_f32 v66, v100, v101
	v_lshlrev_b32_e32 v100, 16, v99
	v_and_b32_e32 v101, 0xffff0000, v99
	v_lshlrev_b32_e32 v52, 16, v67
	v_and_b32_e32 v53, 0xffff0000, v67
	v_pk_mul_f32 v[100:101], v[100:101], v[52:53]
	s_nop 0
	v_cvt_pk_bf16_f32 v67, v100, v101
	global_store_dwordx4 v129, v[64:67], s[88:89] offset:32
	s_waitcnt vmcnt(9) lgkmcnt(0)
	v_lshlrev_b32_e32 v100, 16, v44
	v_and_b32_e32 v101, 0xffff0000, v44
	v_lshlrev_b32_e32 v52, 16, v68
	v_and_b32_e32 v53, 0xffff0000, v68
	v_pk_mul_f32 v[100:101], v[100:101], v[52:53]
	s_nop 0
	v_cvt_pk_bf16_f32 v68, v100, v101
	v_lshlrev_b32_e32 v100, 16, v45
	v_and_b32_e32 v101, 0xffff0000, v45
	v_lshlrev_b32_e32 v52, 16, v69
	v_and_b32_e32 v53, 0xffff0000, v69
	v_pk_mul_f32 v[100:101], v[100:101], v[52:53]
	s_nop 0
	v_cvt_pk_bf16_f32 v69, v100, v101
	v_lshlrev_b32_e32 v100, 16, v46
	v_and_b32_e32 v101, 0xffff0000, v46
	v_lshlrev_b32_e32 v52, 16, v70
	v_and_b32_e32 v53, 0xffff0000, v70
	v_pk_mul_f32 v[100:101], v[100:101], v[52:53]
	s_nop 0
	v_cvt_pk_bf16_f32 v70, v100, v101
	v_lshlrev_b32_e32 v100, 16, v47
	v_and_b32_e32 v101, 0xffff0000, v47
	v_lshlrev_b32_e32 v52, 16, v71
	v_and_b32_e32 v53, 0xffff0000, v71
	v_pk_mul_f32 v[100:101], v[100:101], v[52:53]
	s_nop 0
	v_cvt_pk_bf16_f32 v71, v100, v101
	global_store_dwordx4 v129, v[68:71], s[88:89] offset:48
	s_nop 1
	global_load_dwordx4 v[56:59], v251, s[10:11]
	global_load_dwordx4 v[60:63], v251, s[12:13]
	global_load_dwordx4 v[64:67], v251, s[14:15]
	global_load_dwordx4 v[68:71], v252, s[10:11]
	global_load_dwordx4 v[44:47], v252, s[12:13]
	global_load_dwordx4 v[48:51], v252, s[14:15]
	s_waitcnt vmcnt(13)
	v_lshlrev_b32_e32 v100, 16, v72
	v_and_b32_e32 v101, 0xffff0000, v72
	v_lshlrev_b32_e32 v52, 16, v76
	v_and_b32_e32 v53, 0xffff0000, v76
	v_pk_add_f32 v[100:101], v[100:101], v[52:53]
	v_lshlrev_b32_e32 v52, 16, v80
	v_and_b32_e32 v53, 0xffff0000, v80
	v_pk_mul_f32 v[100:101], v[100:101], v[52:53]
	s_nop 0
	v_cvt_pk_bf16_f32 v72, v100, v101
	v_lshlrev_b32_e32 v100, 16, v73
	v_and_b32_e32 v101, 0xffff0000, v73
	v_lshlrev_b32_e32 v52, 16, v77
	v_and_b32_e32 v53, 0xffff0000, v77
	v_pk_add_f32 v[100:101], v[100:101], v[52:53]
	v_lshlrev_b32_e32 v52, 16, v81
	v_and_b32_e32 v53, 0xffff0000, v81
	v_pk_mul_f32 v[100:101], v[100:101], v[52:53]
	s_nop 0
	v_cvt_pk_bf16_f32 v73, v100, v101
	v_lshlrev_b32_e32 v100, 16, v74
	v_and_b32_e32 v101, 0xffff0000, v74
	v_lshlrev_b32_e32 v52, 16, v78
	v_and_b32_e32 v53, 0xffff0000, v78
	v_pk_add_f32 v[100:101], v[100:101], v[52:53]
	v_lshlrev_b32_e32 v52, 16, v82
	v_and_b32_e32 v53, 0xffff0000, v82
	v_pk_mul_f32 v[100:101], v[100:101], v[52:53]
	s_nop 0
	v_cvt_pk_bf16_f32 v74, v100, v101
	v_lshlrev_b32_e32 v100, 16, v75
	v_and_b32_e32 v101, 0xffff0000, v75
	v_lshlrev_b32_e32 v52, 16, v79
	v_and_b32_e32 v53, 0xffff0000, v79
	v_pk_add_f32 v[100:101], v[100:101], v[52:53]
	v_lshlrev_b32_e32 v52, 16, v83
	v_and_b32_e32 v53, 0xffff0000, v83
	v_pk_mul_f32 v[100:101], v[100:101], v[52:53]
	s_nop 0
	v_cvt_pk_bf16_f32 v75, v100, v101
	global_store_dwordx4 v141, v[72:75], s[90:91]
	s_waitcnt vmcnt(11)
; __device__ __forceinline__ unsigned pk2(float lo, float hi) { const f32x2_t v = {lo, hi}; const bf16v2_t b = __builtin_convertvector(v, bf16v2_t); return __builtin_bit_cast(unsigned, b); }
; __device__ __forceinline__ float bflo(unsigned u) { return __uint_as_float(u << 16); }
; __device__ __forceinline__ float bfhi(unsigned u) { return __uint_as_float(u & 0xffff0000u); }
; __device__ __forceinline__ void ret_out_phase(const Args& A, Frame& F, int l, bool lastl, bf16_t* ARET, bf16_t* ALRU) {
;     ...
; #pragma unroll
;         for (int i = 0; i < 4; ++i) {
;             const int u = tid + i * NTHREADS, r = u >> 4, c8 = (u & 15) * 8;
;             const size_t o = (rowbase + r) * D + 128 * h + c8;
;             const u32x4 hf = *(const u32x4*)(WSB(WS_HF) + o), hb = *(const u32x4*)(WSB(WS_HB) + o), gg = *(const u32x4*)(WSB(WS_GG) + o);
;             u32x4 ov;
; #pragma unroll
;             for (int e = 0; e < 4; ++e) ov[e] = pk2((bflo(hf[e]) + bflo(hb[e])) * bflo(gg[e]), (bfhi(hf[e]) + bfhi(hb[e])) * bfhi(gg[e]));
;             *(u32x4*)(ALRU + o) = ov;
;         }
	v_lshlrev_b32_e32 v100, 16, v84
	v_and_b32_e32 v101, 0xffff0000, v84
	v_lshlrev_b32_e32 v52, 16, v88
	v_and_b32_e32 v53, 0xffff0000, v88
	v_pk_add_f32 v[100:101], v[100:101], v[52:53]
	v_lshlrev_b32_e32 v52, 16, v92
	v_and_b32_e32 v53, 0xffff0000, v92
	v_pk_mul_f32 v[100:101], v[100:101], v[52:53]
	s_nop 0
	v_cvt_pk_bf16_f32 v84, v100, v101
	v_lshlrev_b32_e32 v100, 16, v85
	v_and_b32_e32 v101, 0xffff0000, v85
	v_lshlrev_b32_e32 v52, 16, v89
	v_and_b32_e32 v53, 0xffff0000, v89
	v_pk_add_f32 v[100:101], v[100:101], v[52:53]
	v_lshlrev_b32_e32 v52, 16, v93
	v_and_b32_e32 v53, 0xffff0000, v93
	v_pk_mul_f32 v[100:101], v[100:101], v[52:53]
	s_nop 0
	v_cvt_pk_bf16_f32 v85, v100, v101
	v_lshlrev_b32_e32 v100, 16, v86
	v_and_b32_e32 v101, 0xffff0000, v86
	v_lshlrev_b32_e32 v52, 16, v90
	v_and_b32_e32 v53, 0xffff0000, v90
	v_pk_add_f32 v[100:101], v[100:101], v[52:53]
	v_lshlrev_b32_e32 v52, 16, v94
	v_and_b32_e32 v53, 0xffff0000, v94
	v_pk_mul_f32 v[100:101], v[100:101], v[52:53]
	s_nop 0
	v_cvt_pk_bf16_f32 v86, v100, v101
	v_lshlrev_b32_e32 v100, 16, v87
	v_and_b32_e32 v101, 0xffff0000, v87
	v_lshlrev_b32_e32 v52, 16, v91
	v_and_b32_e32 v53, 0xffff0000, v91
	v_pk_add_f32 v[100:101], v[100:101], v[52:53]
	v_lshlrev_b32_e32 v52, 16, v95
	v_and_b32_e32 v53, 0xffff0000, v95
	v_pk_mul_f32 v[100:101], v[100:101], v[52:53]
	s_nop 0
	v_cvt_pk_bf16_f32 v87, v100, v101
	global_store_dwordx4 v250, v[84:87], s[90:91]
	s_waitcnt vmcnt(5)
	v_lshlrev_b32_e32 v100, 16, v56
	v_and_b32_e32 v101, 0xffff0000, v56
	v_lshlrev_b32_e32 v52, 16, v60
	v_and_b32_e32 v53, 0xffff0000, v60
	v_pk_add_f32 v[100:101], v[100:101], v[52:53]
	v_lshlrev_b32_e32 v52, 16, v64
	v_and_b32_e32 v53, 0xffff0000, v64
	v_pk_mul_f32 v[100:101], v[100:101], v[52:53]
	s_nop 0
	v_cvt_pk_bf16_f32 v56, v100, v101
	v_lshlrev_b32_e32 v100, 16, v57
	v_and_b32_e32 v101, 0xffff0000, v57
	v_lshlrev_b32_e32 v52, 16, v61
	v_and_b32_e32 v53, 0xffff0000, v61
	v_pk_add_f32 v[100:101], v[100:101], v[52:53]
	v_lshlrev_b32_e32 v52, 16, v65
	v_and_b32_e32 v53, 0xffff0000, v65
	v_pk_mul_f32 v[100:101], v[100:101], v[52:53]
	s_nop 0
	v_cvt_pk_bf16_f32 v57, v100, v101
	v_lshlrev_b32_e32 v100, 16, v58
	v_and_b32_e32 v101, 0xffff0000, v58
	v_lshlrev_b32_e32 v52, 16, v62
	v_and_b32_e32 v53, 0xffff0000, v62
	v_pk_add_f32 v[100:101], v[100:101], v[52:53]
	v_lshlrev_b32_e32 v52, 16, v66
	v_and_b32_e32 v53, 0xffff0000, v66
	v_pk_mul_f32 v[100:101], v[100:101], v[52:53]
	s_nop 0
	v_cvt_pk_bf16_f32 v58, v100, v101
	v_lshlrev_b32_e32 v100, 16, v59
	v_and_b32_e32 v101, 0xffff0000, v59
	v_lshlrev_b32_e32 v52, 16, v63
	v_and_b32_e32 v53, 0xffff0000, v63
	v_pk_add_f32 v[100:101], v[100:101], v[52:53]
	v_lshlrev_b32_e32 v52, 16, v67
	v_and_b32_e32 v53, 0xffff0000, v67
	v_pk_mul_f32 v[100:101], v[100:101], v[52:53]
	s_nop 0
	v_cvt_pk_bf16_f32 v59, v100, v101
	global_store_dwordx4 v251, v[56:59], s[90:91]
	s_waitcnt vmcnt(3)
	v_lshlrev_b32_e32 v100, 16, v68
	v_and_b32_e32 v101, 0xffff0000, v68
	v_lshlrev_b32_e32 v52, 16, v44
	v_and_b32_e32 v53, 0xffff0000, v44
	v_pk_add_f32 v[100:101], v[100:101], v[52:53]
	v_lshlrev_b32_e32 v52, 16, v48
	v_and_b32_e32 v53, 0xffff0000, v48
	v_pk_mul_f32 v[100:101], v[100:101], v[52:53]
	s_nop 0
	v_cvt_pk_bf16_f32 v68, v100, v101
	v_lshlrev_b32_e32 v100, 16, v69
	v_and_b32_e32 v101, 0xffff0000, v69
	v_lshlrev_b32_e32 v52, 16, v45
	v_and_b32_e32 v53, 0xffff0000, v45
	v_pk_add_f32 v[100:101], v[100:101], v[52:53]
	v_lshlrev_b32_e32 v52, 16, v49
	v_and_b32_e32 v53, 0xffff0000, v49
	v_pk_mul_f32 v[100:101], v[100:101], v[52:53]
	s_nop 0
	v_cvt_pk_bf16_f32 v69, v100, v101
	v_lshlrev_b32_e32 v100, 16, v70
	v_and_b32_e32 v101, 0xffff0000, v70
	v_lshlrev_b32_e32 v52, 16, v46
	v_and_b32_e32 v53, 0xffff0000, v46
	v_pk_add_f32 v[100:101], v[100:101], v[52:53]
	v_lshlrev_b32_e32 v52, 16, v50
	v_and_b32_e32 v53, 0xffff0000, v50
	v_pk_mul_f32 v[100:101], v[100:101], v[52:53]
	s_nop 0
	v_cvt_pk_bf16_f32 v70, v100, v101
	v_lshlrev_b32_e32 v100, 16, v71
	v_and_b32_e32 v101, 0xffff0000, v71
	v_lshlrev_b32_e32 v52, 16, v47
	v_and_b32_e32 v53, 0xffff0000, v47
	v_pk_add_f32 v[100:101], v[100:101], v[52:53]
	v_lshlrev_b32_e32 v52, 16, v51
	v_and_b32_e32 v53, 0xffff0000, v51
	v_pk_mul_f32 v[100:101], v[100:101], v[52:53]
	s_nop 0
	v_cvt_pk_bf16_f32 v71, v100, v101
	global_store_dwordx4 v252, v[68:71], s[90:91]
	s_cbranch_scc1 .LBB0_30
